# ret_chunk: hoist K-fragment loads of tiles 1-3, batch the 8 V staging loads, epilogue loads hoisted
# baseline (speedup 1.0000x reference)
.LBB0_436:
	s_mov_b64 s[0:1], 0xc000
	v_lshl_add_u64 v[2:3], v[8:9], 0, s[0:1]
	s_mov_b32 s0, 0xc000
	v_mov_b32_e32 v7, v38
	v_cvt_pk_bf16_f32 v38, v6, v38
	v_cvt_pk_bf16_f32 v39, v10, v36
	v_cvt_pk_bf16_f32 v40, v12, v34
	v_cvt_pk_bf16_f32 v41, v14, v32
	v_add_co_u32_e32 v8, vcc, s0, v8
	v_mov_b32_e32 v17, v30
	v_mov_b32_e32 v15, v32
	v_cvt_pk_bf16_f32 v30, v16, v30
	v_cvt_pk_bf16_f32 v31, v18, v28
	v_cvt_pk_bf16_f32 v32, v20, v26
	v_cvt_pk_bf16_f32 v33, v22, v24
	ds_write_b128 v0, v[38:41] offset:49152
	ds_write_b128 v0, v[30:33] offset:49168
	v_addc_co_u32_e32 v9, vcc, 0, v9, vcc
	v_mov_b32_e32 v21, v26
	v_mov_b32_e32 v19, v28
	global_load_dwordx4 v[26:29], v[8:9], off
	global_load_dwordx4 v[30:33], v[2:3], off offset:16
	v_mov_b32_e32 v11, v36
	v_mov_b32_e32 v13, v34
	v_mov_b32_e32 v23, v24
	v_and_b32_e32 v25, 31, v46
	v_ashrrev_i32_e32 v156, 8, v46
	v_bfe_u32 v154, v46, 5, 1
	v_lshlrev_b32_e32 v112, 5, v154
	s_mov_b64 s[0:1], 0x240000
	v_mad_i32_i24 v100, v154, -4, -2
	v_mad_i32_i24 v101, v154, -4, -3
	v_mad_i32_i24 v102, v154, -4, -8
	v_mad_i32_i24 v103, v154, -4, -9
	v_mad_i32_i24 v104, v154, -4, -10
	v_mad_i32_i24 v105, v154, -4, -11
	v_mad_i32_i24 v106, v154, -4, -16
	v_mad_i32_i24 v119, v154, -4, v239
	v_mad_i32_i24 v121, v154, -4, v247
	v_mad_i32_i24 v120, v154, -4, v242
	v_bfe_u32 v110, v46, 2, 2
	v_lshlrev_b32_e32 v113, 15, v156
	s_lshl_b32 s48, s69, 1
	s_waitcnt vmcnt(0)
	v_lshlrev_b32_e32 v2, 16, v26
	v_and_b32_e32 v3, 0xffff0000, v26
	v_pk_fma_f32 v[2:3], v[4:5], v[6:7], v[2:3] op_sel_hi:[0,1,1]
	v_lshlrev_b32_e32 v6, 16, v27
	v_and_b32_e32 v7, 0xffff0000, v27
	v_pk_fma_f32 v[6:7], v[4:5], v[10:11], v[6:7] op_sel_hi:[0,1,1]
	v_lshlrev_b32_e32 v8, 16, v28
	v_and_b32_e32 v9, 0xffff0000, v28
	v_lshlrev_b32_e32 v10, 16, v29
	v_and_b32_e32 v11, 0xffff0000, v29
	v_pk_fma_f32 v[8:9], v[4:5], v[12:13], v[8:9] op_sel_hi:[0,1,1]
	v_pk_fma_f32 v[10:11], v[4:5], v[14:15], v[10:11] op_sel_hi:[0,1,1]
	v_lshlrev_b32_e32 v12, 16, v30
	v_and_b32_e32 v13, 0xffff0000, v30
	v_lshlrev_b32_e32 v14, 16, v31
	v_and_b32_e32 v15, 0xffff0000, v31
	v_pk_fma_f32 v[12:13], v[4:5], v[16:17], v[12:13] op_sel_hi:[0,1,1]
	v_pk_fma_f32 v[14:15], v[4:5], v[18:19], v[14:15] op_sel_hi:[0,1,1]
	v_lshlrev_b32_e32 v16, 16, v32
	v_and_b32_e32 v17, 0xffff0000, v32
	v_lshlrev_b32_e32 v18, 16, v33
	v_and_b32_e32 v19, 0xffff0000, v33
	v_pk_fma_f32 v[16:17], v[4:5], v[20:21], v[16:17] op_sel_hi:[0,1,1]
	v_pk_fma_f32 v[18:19], v[4:5], v[22:23], v[18:19] op_sel_hi:[0,1,1]
	v_cvt_pk_bf16_f32 v2, v2, v3
	v_cvt_pk_bf16_f32 v3, v6, v7
	v_cvt_pk_bf16_f32 v4, v8, v9
	v_cvt_pk_bf16_f32 v5, v10, v11
	v_cvt_pk_bf16_f32 v6, v12, v13
	v_cvt_pk_bf16_f32 v7, v14, v15
	v_cvt_pk_bf16_f32 v8, v16, v17
	v_cvt_pk_bf16_f32 v9, v18, v19
	ds_write_b128 v0, v[2:5] offset:16384
	ds_write_b128 v0, v[6:9] offset:16400
	v_lshrrev_b32_e32 v0, 1, v46
	v_and_or_b32 v155, v0, s70, v25
	v_lshl_add_u32 v8, v156, 7, s89
	v_or_b32_e32 v0, v8, v155
	v_lshrrev_b32_e32 v2, 8, v8
	v_mul_i32_i24_e32 v146, 38, v2
	v_lshlrev_b32_e32 v0, 8, v0
	v_lshl_or_b32 v9, s85, 6, v112
	v_and_b32_e32 v157, 0xff00, v0
	v_ashrrev_i32_e32 v147, 31, v146
	v_or_b32_e32 v0, v157, v9
	v_lshlrev_b64 v[2:3], 17, v[146:147]
	v_lshlrev_b32_e32 v0, 1, v0
	v_lshl_add_u64 v[2:3], s[36:37], 0, v[2:3]
	v_lshl_add_u64 v[4:5], v[2:3], 0, v[0:1]
	v_lshlrev_b32_e32 v0, 1, v46
	v_and_b32_e32 v114, 32, v0
	v_lshlrev_b32_e32 v0, 3, v46
	v_lshl_add_u64 v[6:7], v[4:5], 0, s[0:1]
	s_mov_b32 s0, 0x240000
	v_and_b32_e32 v111, 24, v0
	v_or_b32_e32 v0, v8, v25
	v_add_co_u32_e32 v4, vcc, s0, v4
	v_lshlrev_b32_e32 v0, 8, v0
	s_mov_b32 s0, 0x9f00
	v_and_or_b32 v0, v0, s0, v9
	v_lshlrev_b32_e32 v0, 1, v0
	v_addc_co_u32_e32 v5, vcc, 0, v5, vcc
	v_lshl_add_u64 v[98:99], v[2:3], 0, v[0:1]
	v_add_co_u32_e32 v2, vcc, s96, v98
	s_waitcnt lgkmcnt(0)
	s_nop 0
	v_addc_co_u32_e32 v3, vcc, 0, v99, vcc
	s_barrier
	global_load_dwordx4 v[94:97], v[4:5], off
	global_load_dwordx4 v[82:85], v[6:7], off offset:48
	global_load_dwordx4 v[86:89], v[6:7], off offset:32
	global_load_dwordx4 v[90:93], v[6:7], off offset:16
	v_lshl_add_u64 v[6:7], v[98:99], 0, s[30:31]
	global_load_dwordx4 v[2:5], v[2:3], off
	s_nop 0
	global_load_dwordx4 v[22:25], v[6:7], off offset:16
	global_load_dwordx4 v[26:29], v[6:7], off offset:32
	global_load_dwordx4 v[30:33], v[6:7], off offset:48
	s_mov_b32 s7, 0
	s_mov_b32 s6, 0x264000
	v_lshl_add_u64 v[142:143], v[98:99], 0, s[6:7]
	global_load_dwordx4 v[184:187], v[142:143], off
	global_load_dwordx4 v[188:191], v[142:143], off offset:16
	global_load_dwordx4 v[192:195], v[142:143], off offset:32
	global_load_dwordx4 v[196:199], v[142:143], off offset:48
	s_mov_b32 s6, 0x268000
	v_lshl_add_u64 v[142:143], v[98:99], 0, s[6:7]
	global_load_dwordx4 v[200:203], v[142:143], off
	global_load_dwordx4 v[204:207], v[142:143], off offset:16
	global_load_dwordx4 v[208:211], v[142:143], off offset:32
	global_load_dwordx4 v[212:215], v[142:143], off offset:48
	s_mov_b32 s6, 0x26c000
	v_lshl_add_u64 v[142:143], v[98:99], 0, s[6:7]
	global_load_dwordx4 v[216:219], v[142:143], off
	global_load_dwordx4 v[220:223], v[142:143], off offset:16
	global_load_dwordx4 v[134:137], v[142:143], off offset:32
	global_load_dwordx4 v[138:141], v[142:143], off offset:48
	v_mad_i32_i24 v0, v154, -4, v155
	v_sub_u32_e32 v18, 0, v0
	v_max_i32_e32 v18, v0, v18
	v_cvt_f32_u32_e32 v18, v18
	v_cmp_gt_i32_e32 vcc, 0, v0
	v_add3_u32 v20, 0, v113, v114
	s_mov_b32 s0, 0x264000
	v_cndmask_b32_e32 v0, v108, v109, vcc
	s_waitcnt vmcnt(15)
	v_mfma_f32_32x32x16_bf16 v[2:17], v[2:5], v[94:97], 0
	v_mul_f32_e32 v19, v0, v18
	v_cmp_gt_f32_e32 vcc, s97, v19
	v_lshlrev_b32_e32 v150, 16, v94
	v_and_b32_e32 v151, 0xffff0000, v94
	v_cndmask_b32_e32 v19, 0, v233, vcc
	v_fmac_f32_e32 v19, v0, v18
	v_exp_f32_e32 v0, v19
	s_waitcnt vmcnt(14)
	v_mfma_f32_32x32x16_bf16 v[2:17], v[22:25], v[90:93], v[2:17]
	v_cndmask_b32_e32 v18, 0, v236, vcc
	v_ldexp_f32 v18, v0, v18
	v_mad_i32_i24 v0, v154, -4, -1
	v_add_u32_e32 v19, v0, v155
	v_sub_u32_e32 v21, 0, v19
	v_max_i32_e32 v21, v19, v21
	s_waitcnt vmcnt(13)
	v_mfma_f32_32x32x16_bf16 v[2:17], v[26:29], v[86:89], v[2:17]
	v_cvt_f32_u32_e32 v21, v21
	v_cmp_gt_i32_e32 vcc, 0, v19
	s_nop 1
	v_cndmask_b32_e32 v19, v108, v109, vcc
	v_mul_f32_e32 v22, v19, v21
	v_cmp_gt_f32_e32 vcc, s97, v22
	s_waitcnt vmcnt(12)
	v_mfma_f32_32x32x16_bf16 v[2:17], v[30:33], v[82:85], v[2:17]
	v_cndmask_b32_e32 v22, 0, v233, vcc
	v_fmac_f32_e32 v22, v19, v21
	v_exp_f32_e32 v19, v22
	v_cndmask_b32_e32 v21, 0, v236, vcc
	v_ldexp_f32 v19, v19, v21
	s_nop 6
	v_pk_mul_f32 v[2:3], v[18:19], v[2:3]
	v_add_u32_e32 v18, v100, v155
	v_sub_u32_e32 v19, 0, v18
	v_max_i32_e32 v19, v18, v19
	v_cvt_f32_u32_e32 v19, v19
	v_cmp_gt_i32_e32 vcc, 0, v18
	v_cvt_pk_bf16_f32 v50, v2, v3
	v_lshlrev_b32_e32 v2, 8, v110
	v_cndmask_b32_e32 v18, v108, v109, vcc
	v_mul_f32_e32 v21, v18, v19
	v_cmp_gt_f32_e32 vcc, s97, v21
	v_lshl_or_b32 v2, v154, 10, v2
	v_add3_u32 v115, v20, v111, v2
	v_cndmask_b32_e32 v21, 0, v233, vcc
	v_fmac_f32_e32 v21, v18, v19
	v_exp_f32_e32 v18, v21
	v_cndmask_b32_e32 v19, 0, v236, vcc
	v_ldexp_f32 v18, v18, v19
	v_add_u32_e32 v19, v101, v155
	v_sub_u32_e32 v21, 0, v19
	v_max_i32_e32 v21, v19, v21
	v_cvt_f32_u32_e32 v21, v21
	v_cmp_gt_i32_e32 vcc, 0, v19
	s_nop 1
	v_cndmask_b32_e32 v19, v108, v109, vcc
	v_mul_f32_e32 v22, v19, v21
	v_cmp_gt_f32_e32 vcc, s97, v22
	s_nop 1
	v_cndmask_b32_e32 v22, 0, v233, vcc
	v_fmac_f32_e32 v22, v19, v21
	v_exp_f32_e32 v19, v22
	v_cndmask_b32_e32 v21, 0, v236, vcc
	v_ldexp_f32 v19, v19, v21
	v_pk_mul_f32 v[4:5], v[18:19], v[4:5]
	v_add_u32_e32 v18, v102, v155
	v_sub_u32_e32 v19, 0, v18
	v_max_i32_e32 v19, v18, v19
	v_cvt_f32_u32_e32 v19, v19
	v_cmp_gt_i32_e32 vcc, 0, v18
	v_cvt_pk_bf16_f32 v51, v4, v5
	ds_read_b64_tr_b16 v[2:3], v115
	ds_read_b64_tr_b16 v[4:5], v115 offset:2048
	v_cndmask_b32_e32 v18, v108, v109, vcc
	v_mul_f32_e32 v21, v18, v19
	v_cmp_gt_f32_e32 vcc, s97, v21
	s_nop 1
	v_cndmask_b32_e32 v21, 0, v233, vcc
	v_fmac_f32_e32 v21, v18, v19
	v_exp_f32_e32 v18, v21
	v_cndmask_b32_e32 v19, 0, v236, vcc
	v_ldexp_f32 v18, v18, v19
	v_add_u32_e32 v19, v103, v155
	v_sub_u32_e32 v21, 0, v19
	v_max_i32_e32 v21, v19, v21
	v_cvt_f32_u32_e32 v21, v21
	v_cmp_gt_i32_e32 vcc, 0, v19
	s_nop 1
	v_cndmask_b32_e32 v19, v108, v109, vcc
	v_mul_f32_e32 v22, v19, v21
	v_cmp_gt_f32_e32 vcc, s97, v22
	s_nop 1
	v_cndmask_b32_e32 v22, 0, v233, vcc
	v_fmac_f32_e32 v22, v19, v21
	v_exp_f32_e32 v19, v22
	v_cndmask_b32_e32 v21, 0, v236, vcc
	v_ldexp_f32 v19, v19, v21
	v_pk_mul_f32 v[6:7], v[18:19], v[6:7]
	v_add_u32_e32 v18, v104, v155
	v_sub_u32_e32 v19, 0, v18
	v_max_i32_e32 v19, v18, v19
	v_cvt_f32_u32_e32 v19, v19
	v_cmp_gt_i32_e32 vcc, 0, v18
	v_cvt_pk_bf16_f32 v52, v6, v7
	s_nop 0
	v_cndmask_b32_e32 v18, v108, v109, vcc
	v_mul_f32_e32 v21, v18, v19
	v_cmp_gt_f32_e32 vcc, s97, v21
	s_nop 1
	v_cndmask_b32_e32 v21, 0, v233, vcc
	v_fmac_f32_e32 v21, v18, v19
	v_exp_f32_e32 v18, v21
	v_cndmask_b32_e32 v19, 0, v236, vcc
	v_ldexp_f32 v18, v18, v19
	v_add_u32_e32 v19, v105, v155
	v_sub_u32_e32 v21, 0, v19
	v_max_i32_e32 v21, v19, v21
	v_cvt_f32_u32_e32 v21, v21
	v_cmp_gt_i32_e32 vcc, 0, v19
	s_nop 1
	v_cndmask_b32_e32 v19, v108, v109, vcc
	v_mul_f32_e32 v22, v19, v21
	v_cmp_gt_f32_e32 vcc, s97, v22
	s_nop 1
	v_cndmask_b32_e32 v22, 0, v233, vcc
	v_fmac_f32_e32 v22, v19, v21
	v_exp_f32_e32 v19, v22
	v_cndmask_b32_e32 v21, 0, v236, vcc
	v_ldexp_f32 v19, v19, v21
	v_pk_mul_f32 v[8:9], v[18:19], v[8:9]
	v_add_u32_e32 v18, v106, v155
	v_sub_u32_e32 v19, 0, v18
	v_max_i32_e32 v19, v18, v19
	v_cvt_f32_u32_e32 v19, v19
	v_cmp_gt_i32_e32 vcc, 0, v18
	v_cvt_pk_bf16_f32 v53, v8, v9
	s_nop 0
	v_cndmask_b32_e32 v18, v108, v109, vcc
	v_mul_f32_e32 v21, v18, v19
	v_cmp_gt_f32_e32 vcc, s97, v21
	s_nop 1
	v_cndmask_b32_e32 v21, 0, v233, vcc
	v_fmac_f32_e32 v21, v18, v19
	v_exp_f32_e32 v18, v21
	v_cndmask_b32_e32 v19, 0, v236, vcc
	v_ldexp_f32 v18, v18, v19
	v_not_b32_e32 v19, 16
	v_mad_i32_i24 v107, v154, -4, v19
	v_add_u32_e32 v19, v107, v155
	v_sub_u32_e32 v21, 0, v19
	v_max_i32_e32 v21, v19, v21
	v_cvt_f32_u32_e32 v21, v21
	v_cmp_gt_i32_e32 vcc, 0, v19
	s_nop 1
	v_cndmask_b32_e32 v19, v108, v109, vcc
	v_mul_f32_e32 v22, v19, v21
	v_cmp_gt_f32_e32 vcc, s97, v22
	s_nop 1
	v_cndmask_b32_e32 v22, 0, v233, vcc
	v_fmac_f32_e32 v22, v19, v21
	v_exp_f32_e32 v19, v22
	v_cndmask_b32_e32 v21, 0, v236, vcc
	v_ldexp_f32 v19, v19, v21
	v_pk_mul_f32 v[10:11], v[18:19], v[10:11]
	v_not_b32_e32 v18, 17
	v_mad_i32_i24 v116, v154, -4, v18
	v_add_u32_e32 v18, v116, v155
	v_sub_u32_e32 v19, 0, v18
	v_max_i32_e32 v19, v18, v19
	v_cvt_f32_u32_e32 v19, v19
	v_cmp_gt_i32_e32 vcc, 0, v18
	v_cvt_pk_bf16_f32 v66, v10, v11
	s_nop 0
	v_cndmask_b32_e32 v18, v108, v109, vcc
	v_mul_f32_e32 v21, v18, v19
	v_cmp_gt_f32_e32 vcc, s97, v21
	s_nop 1
	v_cndmask_b32_e32 v21, 0, v233, vcc
	v_fmac_f32_e32 v21, v18, v19
	v_exp_f32_e32 v18, v21
	v_cndmask_b32_e32 v19, 0, v236, vcc
	v_ldexp_f32 v18, v18, v19
	v_not_b32_e32 v19, 18
	v_mad_i32_i24 v117, v154, -4, v19
	v_add_u32_e32 v19, v117, v155
	v_sub_u32_e32 v21, 0, v19
	v_max_i32_e32 v21, v19, v21
	v_cvt_f32_u32_e32 v21, v21
	v_cmp_gt_i32_e32 vcc, 0, v19
	s_nop 1
	v_cndmask_b32_e32 v19, v108, v109, vcc
	v_mul_f32_e32 v22, v19, v21
	v_cmp_gt_f32_e32 vcc, s97, v22
	s_nop 1
	v_cndmask_b32_e32 v22, 0, v233, vcc
	v_fmac_f32_e32 v22, v19, v21
	v_exp_f32_e32 v19, v22
	v_cndmask_b32_e32 v21, 0, v236, vcc
	v_ldexp_f32 v19, v19, v21
	v_pk_mul_f32 v[12:13], v[18:19], v[12:13]
	v_not_b32_e32 v18, 23
	v_mad_i32_i24 v118, v154, -4, v18
	v_add_u32_e32 v18, v118, v155
	v_sub_u32_e32 v19, 0, v18
	v_max_i32_e32 v19, v18, v19
	v_cvt_f32_u32_e32 v19, v19
	v_cmp_gt_i32_e32 vcc, 0, v18
	v_cvt_pk_bf16_f32 v67, v12, v13
	s_nop 0
	v_cndmask_b32_e32 v18, v108, v109, vcc
	v_mul_f32_e32 v21, v18, v19
	v_cmp_gt_f32_e32 vcc, s97, v21
	s_nop 1
	v_cndmask_b32_e32 v21, 0, v233, vcc
	v_fmac_f32_e32 v21, v18, v19
	v_exp_f32_e32 v18, v21
	v_cndmask_b32_e32 v19, 0, v236, vcc
	v_ldexp_f32 v18, v18, v19
	v_add_u32_e32 v19, v119, v155
	v_sub_u32_e32 v21, 0, v19
	v_max_i32_e32 v21, v19, v21
	v_cvt_f32_u32_e32 v21, v21
	v_cmp_gt_i32_e32 vcc, 0, v19
	s_nop 1
	v_cndmask_b32_e32 v19, v108, v109, vcc
	v_mul_f32_e32 v22, v19, v21
	v_cmp_gt_f32_e32 vcc, s97, v22
	s_nop 1
	v_cndmask_b32_e32 v22, 0, v233, vcc
	v_fmac_f32_e32 v22, v19, v21
	v_exp_f32_e32 v19, v22
	v_cndmask_b32_e32 v21, 0, v236, vcc
	v_ldexp_f32 v19, v19, v21
	v_pk_mul_f32 v[14:15], v[18:19], v[14:15]
	v_add_u32_e32 v18, v121, v155
	v_sub_u32_e32 v19, 0, v18
	v_max_i32_e32 v19, v18, v19
	v_cvt_f32_u32_e32 v19, v19
	v_cmp_gt_i32_e32 vcc, 0, v18
	v_cvt_pk_bf16_f32 v68, v14, v15
	s_nop 0
	v_cndmask_b32_e32 v18, v108, v109, vcc
	v_mul_f32_e32 v21, v18, v19
	v_cmp_gt_f32_e32 vcc, s97, v21
	s_nop 1
	v_cndmask_b32_e32 v21, 0, v233, vcc
	v_fmac_f32_e32 v21, v18, v19
	v_exp_f32_e32 v18, v21
	v_cndmask_b32_e32 v19, 0, v236, vcc
	v_ldexp_f32 v18, v18, v19
	v_add_u32_e32 v19, v120, v155
	v_sub_u32_e32 v21, 0, v19
	v_max_i32_e32 v21, v19, v21
	v_cvt_f32_u32_e32 v21, v21
	v_cmp_gt_i32_e32 vcc, 0, v19
	s_nop 1
	v_cndmask_b32_e32 v19, v108, v109, vcc
	v_mul_f32_e32 v22, v19, v21
	v_cmp_gt_f32_e32 vcc, s97, v22
	s_nop 1
	v_cndmask_b32_e32 v22, 0, v233, vcc
	v_fmac_f32_e32 v22, v19, v21
	v_exp_f32_e32 v19, v22
	v_cndmask_b32_e32 v21, 0, v236, vcc
	v_ldexp_f32 v19, v19, v21
	v_pk_mul_f32 v[16:17], v[18:19], v[16:17]
	ds_read_b64_tr_b16 v[18:19], v115 offset:4096
	ds_read_b64_tr_b16 v[20:21], v115 offset:6144
	v_cvt_pk_bf16_f32 v69, v16, v17
	s_waitcnt lgkmcnt(2)
	v_mfma_f32_32x32x16_bf16 v[2:17], v[2:5], v[50:53], 0
	s_waitcnt lgkmcnt(0)
	v_mfma_f32_32x32x16_bf16 v[2:17], v[18:21], v[66:69], v[2:17]
	ds_read_b64_tr_b16 v[18:19], v115 offset:64
	ds_read_b64_tr_b16 v[20:21], v115 offset:2112
	ds_read_b64_tr_b16 v[34:35], v115 offset:4160
	ds_read_b64_tr_b16 v[36:37], v115 offset:6208
	s_waitcnt lgkmcnt(2)
	v_mfma_f32_32x32x16_bf16 v[18:33], v[18:21], v[50:53], 0
	s_waitcnt lgkmcnt(0)
	v_mfma_f32_32x32x16_bf16 v[18:33], v[34:37], v[66:69], v[18:33]
	ds_read_b64_tr_b16 v[34:35], v115 offset:128
	ds_read_b64_tr_b16 v[36:37], v115 offset:2176
	ds_read_b64_tr_b16 v[54:55], v115 offset:4224
	ds_read_b64_tr_b16 v[56:57], v115 offset:6272
	s_waitcnt lgkmcnt(2)
	v_mfma_f32_32x32x16_bf16 v[34:49], v[34:37], v[50:53], 0
	s_waitcnt lgkmcnt(0)
	v_mfma_f32_32x32x16_bf16 v[34:49], v[54:57], v[66:69], v[34:49]
	ds_read_b64_tr_b16 v[54:55], v115 offset:192
	ds_read_b64_tr_b16 v[56:57], v115 offset:2240
	ds_read_b64_tr_b16 v[70:71], v115 offset:4288
	ds_read_b64_tr_b16 v[72:73], v115 offset:6336
	s_waitcnt lgkmcnt(2)
	v_mfma_f32_32x32x16_bf16 v[50:65], v[54:57], v[50:53], 0
	s_waitcnt lgkmcnt(0)
	v_mfma_f32_32x32x16_bf16 v[50:65], v[70:73], v[66:69], v[50:65]
	s_mov_b32 s0, 0x268000
	s_nop 0
	s_waitcnt vmcnt(11)
	v_mfma_f32_32x32x16_bf16 v[66:81], v[184:187], v[94:97], 0
	s_waitcnt vmcnt(10)
	v_mfma_f32_32x32x16_bf16 v[66:81], v[188:191], v[90:93], v[66:81]
	v_subrev_u32_e32 v122, 32, v155
	v_mad_i32_i24 v123, v154, -4, v122
	v_sub_u32_e32 v124, 0, v123
	v_max_i32_e32 v124, v123, v124
	v_cvt_f32_u32_e32 v124, v124
	v_cmp_gt_i32_e32 vcc, 0, v123
	s_waitcnt vmcnt(9)
	v_mfma_f32_32x32x16_bf16 v[66:81], v[192:195], v[86:89], v[66:81]
	v_cndmask_b32_e32 v123, v108, v109, vcc
	v_mul_f32_e32 v125, v123, v124
	v_cmp_gt_f32_e32 vcc, s97, v125
	s_nop 1
	v_cndmask_b32_e32 v125, 0, v233, vcc
	v_fmac_f32_e32 v125, v123, v124
	v_exp_f32_e32 v123, v125
	v_cndmask_b32_e32 v124, 0, v236, vcc
	s_waitcnt vmcnt(8)
	v_mfma_f32_32x32x16_bf16 v[66:81], v[196:199], v[82:85], v[66:81]
	v_ldexp_f32 v124, v123, v124
	v_add_u32_e32 v123, v122, v0
	v_sub_u32_e32 v125, 0, v123
	v_max_i32_e32 v125, v123, v125
	v_cvt_f32_u32_e32 v125, v125
	v_cmp_gt_i32_e32 vcc, 0, v123
	s_nop 1
	v_cndmask_b32_e32 v123, v108, v109, vcc
	v_mul_f32_e32 v126, v123, v125
	v_cmp_gt_f32_e32 vcc, s97, v126
	s_nop 1
	v_cndmask_b32_e32 v126, 0, v233, vcc
	v_fmac_f32_e32 v126, v123, v125
	v_exp_f32_e32 v123, v126
	v_cndmask_b32_e32 v125, 0, v236, vcc
	v_ldexp_f32 v125, v123, v125
	v_add_u32_e32 v123, v122, v100
	v_pk_mul_f32 v[66:67], v[124:125], v[66:67]
	v_sub_u32_e32 v124, 0, v123
	v_max_i32_e32 v124, v123, v124
	v_cvt_f32_u32_e32 v124, v124
	v_cmp_gt_i32_e32 vcc, 0, v123
	v_cvt_pk_bf16_f32 v66, v66, v67
	s_nop 0
	v_cndmask_b32_e32 v123, v108, v109, vcc
	v_mul_f32_e32 v125, v123, v124
	v_cmp_gt_f32_e32 vcc, s97, v125
	s_nop 1
	v_cndmask_b32_e32 v125, 0, v233, vcc
	v_fmac_f32_e32 v125, v123, v124
	v_exp_f32_e32 v123, v125
	v_cndmask_b32_e32 v124, 0, v236, vcc
	v_ldexp_f32 v124, v123, v124
	v_add_u32_e32 v123, v122, v101
	v_sub_u32_e32 v125, 0, v123
	v_max_i32_e32 v125, v123, v125
	v_cvt_f32_u32_e32 v125, v125
	v_cmp_gt_i32_e32 vcc, 0, v123
	s_nop 1
	v_cndmask_b32_e32 v123, v108, v109, vcc
	v_mul_f32_e32 v126, v123, v125
	v_cmp_gt_f32_e32 vcc, s97, v126
	s_nop 1
	v_cndmask_b32_e32 v126, 0, v233, vcc
	v_fmac_f32_e32 v126, v123, v125
	v_exp_f32_e32 v123, v126
	v_cndmask_b32_e32 v125, 0, v236, vcc
	v_ldexp_f32 v125, v123, v125
	v_add_u32_e32 v123, v122, v102
	v_pk_mul_f32 v[68:69], v[124:125], v[68:69]
	v_sub_u32_e32 v124, 0, v123
	v_max_i32_e32 v124, v123, v124
	v_cvt_f32_u32_e32 v124, v124
	v_cmp_gt_i32_e32 vcc, 0, v123
	v_cvt_pk_bf16_f32 v67, v68, v69
	s_nop 0
	v_cndmask_b32_e32 v123, v108, v109, vcc
	v_mul_f32_e32 v125, v123, v124
	v_cmp_gt_f32_e32 vcc, s97, v125
	s_nop 1
	v_cndmask_b32_e32 v125, 0, v233, vcc
	v_fmac_f32_e32 v125, v123, v124
	v_exp_f32_e32 v123, v125
	v_cndmask_b32_e32 v124, 0, v236, vcc
	v_ldexp_f32 v124, v123, v124
	v_add_u32_e32 v123, v122, v103
	v_sub_u32_e32 v125, 0, v123
	v_max_i32_e32 v125, v123, v125
	v_cvt_f32_u32_e32 v125, v125
	v_cmp_gt_i32_e32 vcc, 0, v123
	s_nop 1
	v_cndmask_b32_e32 v123, v108, v109, vcc
	v_mul_f32_e32 v126, v123, v125
	v_cmp_gt_f32_e32 vcc, s97, v126
	s_nop 1
	v_cndmask_b32_e32 v126, 0, v233, vcc
	v_fmac_f32_e32 v126, v123, v125
	v_exp_f32_e32 v123, v126
	v_cndmask_b32_e32 v125, 0, v236, vcc
	v_ldexp_f32 v125, v123, v125
	v_add_u32_e32 v123, v122, v104
	v_pk_mul_f32 v[70:71], v[124:125], v[70:71]
	v_sub_u32_e32 v124, 0, v123
	v_max_i32_e32 v124, v123, v124
	v_cvt_f32_u32_e32 v124, v124
	v_cmp_gt_i32_e32 vcc, 0, v123
	v_cvt_pk_bf16_f32 v68, v70, v71
	s_nop 0
	v_cndmask_b32_e32 v123, v108, v109, vcc
	v_mul_f32_e32 v125, v123, v124
	v_cmp_gt_f32_e32 vcc, s97, v125
	s_nop 1
	v_cndmask_b32_e32 v125, 0, v233, vcc
	v_fmac_f32_e32 v125, v123, v124
	v_exp_f32_e32 v123, v125
	v_cndmask_b32_e32 v124, 0, v236, vcc
	v_ldexp_f32 v124, v123, v124
	v_add_u32_e32 v123, v122, v105
	v_sub_u32_e32 v125, 0, v123
	v_max_i32_e32 v125, v123, v125
	v_cvt_f32_u32_e32 v125, v125
	v_cmp_gt_i32_e32 vcc, 0, v123
	s_nop 1
	v_cndmask_b32_e32 v123, v108, v109, vcc
	v_mul_f32_e32 v126, v123, v125
	v_cmp_gt_f32_e32 vcc, s97, v126
	s_nop 1
	v_cndmask_b32_e32 v126, 0, v233, vcc
	v_fmac_f32_e32 v126, v123, v125
	v_exp_f32_e32 v123, v126
	v_cndmask_b32_e32 v125, 0, v236, vcc
	v_ldexp_f32 v125, v123, v125
	v_add_u32_e32 v123, v122, v106
	v_pk_mul_f32 v[72:73], v[124:125], v[72:73]
	v_sub_u32_e32 v124, 0, v123
	v_max_i32_e32 v124, v123, v124
	v_cvt_f32_u32_e32 v124, v124
	v_cmp_gt_i32_e32 vcc, 0, v123
	v_cvt_pk_bf16_f32 v69, v72, v73
	s_nop 0
	v_cndmask_b32_e32 v123, v108, v109, vcc
	v_mul_f32_e32 v125, v123, v124
	v_cmp_gt_f32_e32 vcc, s97, v125
	s_nop 1
	v_cndmask_b32_e32 v125, 0, v233, vcc
	v_fmac_f32_e32 v125, v123, v124
	v_exp_f32_e32 v123, v125
	v_cndmask_b32_e32 v124, 0, v236, vcc
	v_ldexp_f32 v124, v123, v124
	v_add_u32_e32 v123, v122, v107
	v_sub_u32_e32 v125, 0, v123
	v_max_i32_e32 v125, v123, v125
	v_cvt_f32_u32_e32 v125, v125
	v_cmp_gt_i32_e32 vcc, 0, v123
	s_nop 1
	v_cndmask_b32_e32 v123, v108, v109, vcc
	v_mul_f32_e32 v126, v123, v125
	v_cmp_gt_f32_e32 vcc, s97, v126
	s_nop 1
	v_cndmask_b32_e32 v126, 0, v233, vcc
	v_fmac_f32_e32 v126, v123, v125
	v_exp_f32_e32 v123, v126
	v_cndmask_b32_e32 v125, 0, v236, vcc
	v_ldexp_f32 v125, v123, v125
	v_add_u32_e32 v123, v122, v116
	v_pk_mul_f32 v[74:75], v[124:125], v[74:75]
	v_sub_u32_e32 v124, 0, v123
	v_max_i32_e32 v124, v123, v124
	v_cvt_f32_u32_e32 v124, v124
	v_cmp_gt_i32_e32 vcc, 0, v123
	v_cvt_pk_bf16_f32 v70, v74, v75
	s_nop 0
	v_cndmask_b32_e32 v123, v108, v109, vcc
	v_mul_f32_e32 v125, v123, v124
	v_cmp_gt_f32_e32 vcc, s97, v125
	s_nop 1
	v_cndmask_b32_e32 v125, 0, v233, vcc
	v_fmac_f32_e32 v125, v123, v124
	v_exp_f32_e32 v123, v125
	v_cndmask_b32_e32 v124, 0, v236, vcc
	v_ldexp_f32 v124, v123, v124
	v_add_u32_e32 v123, v122, v117
	v_sub_u32_e32 v125, 0, v123
	v_max_i32_e32 v125, v123, v125
	v_cvt_f32_u32_e32 v125, v125
	v_cmp_gt_i32_e32 vcc, 0, v123
	s_nop 1
	v_cndmask_b32_e32 v123, v108, v109, vcc
	v_mul_f32_e32 v126, v123, v125
	v_cmp_gt_f32_e32 vcc, s97, v126
	s_nop 1
	v_cndmask_b32_e32 v126, 0, v233, vcc
	v_fmac_f32_e32 v126, v123, v125
	v_exp_f32_e32 v123, v126
	v_cndmask_b32_e32 v125, 0, v236, vcc
	v_ldexp_f32 v125, v123, v125
	v_add_u32_e32 v123, v122, v118
	v_pk_mul_f32 v[76:77], v[124:125], v[76:77]
	v_sub_u32_e32 v124, 0, v123
	v_max_i32_e32 v124, v123, v124
	v_cvt_f32_u32_e32 v124, v124
	v_cmp_gt_i32_e32 vcc, 0, v123
	v_cvt_pk_bf16_f32 v71, v76, v77
	ds_read_b64_tr_b16 v[74:75], v115 offset:8192
	ds_read_b64_tr_b16 v[76:77], v115 offset:10240
	v_cndmask_b32_e32 v123, v108, v109, vcc
	v_mul_f32_e32 v125, v123, v124
	v_cmp_gt_f32_e32 vcc, s97, v125
	s_waitcnt lgkmcnt(0)
	v_mfma_f32_32x32x16_bf16 v[2:17], v[74:77], v[66:69], v[2:17]
	v_cndmask_b32_e32 v125, 0, v233, vcc
	v_fmac_f32_e32 v125, v123, v124
	v_exp_f32_e32 v123, v125
	v_cndmask_b32_e32 v124, 0, v236, vcc
	ds_read_b64_tr_b16 v[74:75], v115 offset:12288
	ds_read_b64_tr_b16 v[76:77], v115 offset:14336
	v_ldexp_f32 v124, v123, v124
	v_add_u32_e32 v123, v122, v119
	v_sub_u32_e32 v125, 0, v123
	v_max_i32_e32 v125, v123, v125
	v_cvt_f32_u32_e32 v125, v125
	v_cmp_gt_i32_e32 vcc, 0, v123
	s_nop 1
	v_cndmask_b32_e32 v123, v108, v109, vcc
	v_mul_f32_e32 v126, v123, v125
	v_cmp_gt_f32_e32 vcc, s97, v126
	s_nop 1
	v_cndmask_b32_e32 v126, 0, v233, vcc
	v_fmac_f32_e32 v126, v123, v125
	v_exp_f32_e32 v123, v126
	v_cndmask_b32_e32 v125, 0, v236, vcc
	v_ldexp_f32 v125, v123, v125
	v_add_u32_e32 v123, v122, v121
	v_pk_mul_f32 v[78:79], v[124:125], v[78:79]
	v_sub_u32_e32 v124, 0, v123
	v_max_i32_e32 v124, v123, v124
	v_cvt_f32_u32_e32 v124, v124
	v_cmp_gt_i32_e32 vcc, 0, v123
	v_add_u32_e32 v122, v122, v120
	v_cvt_pk_bf16_f32 v72, v78, v79
	v_cndmask_b32_e32 v123, v108, v109, vcc
	v_mul_f32_e32 v125, v123, v124
	v_cmp_gt_f32_e32 vcc, s97, v125
	s_nop 1
	v_cndmask_b32_e32 v125, 0, v233, vcc
	v_fmac_f32_e32 v125, v123, v124
	v_exp_f32_e32 v123, v125
	v_cndmask_b32_e32 v124, 0, v236, vcc
	v_cmp_gt_i32_e32 vcc, 0, v122
	v_ldexp_f32 v124, v123, v124
	v_sub_u32_e32 v123, 0, v122
	v_max_i32_e32 v123, v122, v123
	v_cvt_f32_u32_e32 v123, v123
	v_cndmask_b32_e32 v122, v108, v109, vcc
	v_mul_f32_e32 v125, v122, v123
	v_cmp_gt_f32_e32 vcc, s97, v125
	s_nop 1
	v_cndmask_b32_e32 v125, 0, v233, vcc
	v_fmac_f32_e32 v125, v122, v123
	v_exp_f32_e32 v122, v125
	v_cndmask_b32_e32 v123, 0, v236, vcc
	v_ldexp_f32 v125, v122, v123
	v_pk_mul_f32 v[80:81], v[124:125], v[80:81]
	s_nop 0
	v_cvt_pk_bf16_f32 v73, v80, v81
	s_waitcnt lgkmcnt(0)
	s_nop 0
	v_mfma_f32_32x32x16_bf16 v[2:17], v[74:77], v[70:73], v[2:17]
	ds_read_b64_tr_b16 v[74:75], v115 offset:8256
	ds_read_b64_tr_b16 v[76:77], v115 offset:10304
	s_waitcnt lgkmcnt(0)
	v_mfma_f32_32x32x16_bf16 v[18:33], v[74:77], v[66:69], v[18:33]
	ds_read_b64_tr_b16 v[74:75], v115 offset:12352
	ds_read_b64_tr_b16 v[76:77], v115 offset:14400
	s_waitcnt lgkmcnt(0)
	v_mfma_f32_32x32x16_bf16 v[18:33], v[74:77], v[70:73], v[18:33]
	ds_read_b64_tr_b16 v[74:75], v115 offset:8320
	ds_read_b64_tr_b16 v[76:77], v115 offset:10368
	s_waitcnt lgkmcnt(0)
	v_mfma_f32_32x32x16_bf16 v[34:49], v[74:77], v[66:69], v[34:49]
	ds_read_b64_tr_b16 v[74:75], v115 offset:12416
	ds_read_b64_tr_b16 v[76:77], v115 offset:14464
	s_waitcnt lgkmcnt(0)
	v_mfma_f32_32x32x16_bf16 v[34:49], v[74:77], v[70:73], v[34:49]
	ds_read_b64_tr_b16 v[74:75], v115 offset:8384
	ds_read_b64_tr_b16 v[76:77], v115 offset:10432
	s_waitcnt lgkmcnt(0)
	v_mfma_f32_32x32x16_bf16 v[50:65], v[74:77], v[66:69], v[50:65]
	ds_read_b64_tr_b16 v[66:67], v115 offset:12480
	ds_read_b64_tr_b16 v[68:69], v115 offset:14528
	s_waitcnt lgkmcnt(0)
	v_mfma_f32_32x32x16_bf16 v[50:65], v[66:69], v[70:73], v[50:65]
	s_mov_b32 s0, 0x26c000
	s_nop 0
	s_waitcnt vmcnt(7)
	v_mfma_f32_32x32x16_bf16 v[66:81], v[200:203], v[94:97], 0
	s_waitcnt vmcnt(6)
	v_mfma_f32_32x32x16_bf16 v[66:81], v[204:207], v[90:93], v[66:81]
	v_subrev_u32_e32 v122, 64, v155
	v_mad_i32_i24 v123, v154, -4, v122
	v_sub_u32_e32 v124, 0, v123
	v_max_i32_e32 v124, v123, v124
	v_cvt_f32_u32_e32 v124, v124
	v_cmp_gt_i32_e32 vcc, 0, v123
	s_waitcnt vmcnt(5)
	v_mfma_f32_32x32x16_bf16 v[66:81], v[208:211], v[86:89], v[66:81]
	v_cndmask_b32_e32 v123, v108, v109, vcc
	v_mul_f32_e32 v125, v123, v124
	v_cmp_gt_f32_e32 vcc, s97, v125
	s_nop 1
	v_cndmask_b32_e32 v125, 0, v233, vcc
	v_fmac_f32_e32 v125, v123, v124
	v_exp_f32_e32 v123, v125
	v_cndmask_b32_e32 v124, 0, v236, vcc
	s_waitcnt vmcnt(4)
	v_mfma_f32_32x32x16_bf16 v[66:81], v[212:215], v[82:85], v[66:81]
	v_ldexp_f32 v124, v123, v124
	v_add_u32_e32 v123, v122, v0
	v_sub_u32_e32 v125, 0, v123
	v_max_i32_e32 v125, v123, v125
	v_cvt_f32_u32_e32 v125, v125
	v_cmp_gt_i32_e32 vcc, 0, v123
	s_nop 1
	v_cndmask_b32_e32 v123, v108, v109, vcc
	v_mul_f32_e32 v126, v123, v125
	v_cmp_gt_f32_e32 vcc, s97, v126
	s_nop 1
	v_cndmask_b32_e32 v126, 0, v233, vcc
	v_fmac_f32_e32 v126, v123, v125
	v_exp_f32_e32 v123, v126
	v_cndmask_b32_e32 v125, 0, v236, vcc
	v_ldexp_f32 v125, v123, v125
	v_add_u32_e32 v123, v122, v100
	v_pk_mul_f32 v[66:67], v[124:125], v[66:67]
	v_sub_u32_e32 v124, 0, v123
	v_max_i32_e32 v124, v123, v124
	v_cvt_f32_u32_e32 v124, v124
	v_cmp_gt_i32_e32 vcc, 0, v123
	v_cvt_pk_bf16_f32 v66, v66, v67
	s_nop 0
	v_cndmask_b32_e32 v123, v108, v109, vcc
	v_mul_f32_e32 v125, v123, v124
	v_cmp_gt_f32_e32 vcc, s97, v125
	s_nop 1
	v_cndmask_b32_e32 v125, 0, v233, vcc
	v_fmac_f32_e32 v125, v123, v124
	v_exp_f32_e32 v123, v125
	v_cndmask_b32_e32 v124, 0, v236, vcc
	v_ldexp_f32 v124, v123, v124
	v_add_u32_e32 v123, v122, v101
	v_sub_u32_e32 v125, 0, v123
	v_max_i32_e32 v125, v123, v125
	v_cvt_f32_u32_e32 v125, v125
	v_cmp_gt_i32_e32 vcc, 0, v123
	s_nop 1
	v_cndmask_b32_e32 v123, v108, v109, vcc
	v_mul_f32_e32 v126, v123, v125
	v_cmp_gt_f32_e32 vcc, s97, v126
	s_nop 1
	v_cndmask_b32_e32 v126, 0, v233, vcc
	v_fmac_f32_e32 v126, v123, v125
	v_exp_f32_e32 v123, v126
	v_cndmask_b32_e32 v125, 0, v236, vcc
	v_ldexp_f32 v125, v123, v125
	v_add_u32_e32 v123, v122, v102
	v_pk_mul_f32 v[68:69], v[124:125], v[68:69]
	v_sub_u32_e32 v124, 0, v123
	v_max_i32_e32 v124, v123, v124
	v_cvt_f32_u32_e32 v124, v124
	v_cmp_gt_i32_e32 vcc, 0, v123
	v_cvt_pk_bf16_f32 v67, v68, v69
	s_nop 0
	v_cndmask_b32_e32 v123, v108, v109, vcc
	v_mul_f32_e32 v125, v123, v124
	v_cmp_gt_f32_e32 vcc, s97, v125
	s_nop 1
	v_cndmask_b32_e32 v125, 0, v233, vcc
	v_fmac_f32_e32 v125, v123, v124
	v_exp_f32_e32 v123, v125
	v_cndmask_b32_e32 v124, 0, v236, vcc
	v_ldexp_f32 v124, v123, v124
	v_add_u32_e32 v123, v122, v103
	v_sub_u32_e32 v125, 0, v123
	v_max_i32_e32 v125, v123, v125
	v_cvt_f32_u32_e32 v125, v125
	v_cmp_gt_i32_e32 vcc, 0, v123
	s_nop 1
	v_cndmask_b32_e32 v123, v108, v109, vcc
	v_mul_f32_e32 v126, v123, v125
	v_cmp_gt_f32_e32 vcc, s97, v126
	s_nop 1
	v_cndmask_b32_e32 v126, 0, v233, vcc
	v_fmac_f32_e32 v126, v123, v125
	v_exp_f32_e32 v123, v126
	v_cndmask_b32_e32 v125, 0, v236, vcc
	v_ldexp_f32 v125, v123, v125
	v_add_u32_e32 v123, v122, v104
	v_pk_mul_f32 v[70:71], v[124:125], v[70:71]
	v_sub_u32_e32 v124, 0, v123
	v_max_i32_e32 v124, v123, v124
	v_cvt_f32_u32_e32 v124, v124
	v_cmp_gt_i32_e32 vcc, 0, v123
	v_cvt_pk_bf16_f32 v68, v70, v71
	s_nop 0
	v_cndmask_b32_e32 v123, v108, v109, vcc
	v_mul_f32_e32 v125, v123, v124
	v_cmp_gt_f32_e32 vcc, s97, v125
	s_nop 1
	v_cndmask_b32_e32 v125, 0, v233, vcc
	v_fmac_f32_e32 v125, v123, v124
	v_exp_f32_e32 v123, v125
	v_cndmask_b32_e32 v124, 0, v236, vcc
	v_ldexp_f32 v124, v123, v124
	v_add_u32_e32 v123, v122, v105
	v_sub_u32_e32 v125, 0, v123
	v_max_i32_e32 v125, v123, v125
	v_cvt_f32_u32_e32 v125, v125
	v_cmp_gt_i32_e32 vcc, 0, v123
	s_nop 1
	v_cndmask_b32_e32 v123, v108, v109, vcc
	v_mul_f32_e32 v126, v123, v125
	v_cmp_gt_f32_e32 vcc, s97, v126
	s_nop 1
	v_cndmask_b32_e32 v126, 0, v233, vcc
	v_fmac_f32_e32 v126, v123, v125
	v_exp_f32_e32 v123, v126
	v_cndmask_b32_e32 v125, 0, v236, vcc
	v_ldexp_f32 v125, v123, v125
	v_add_u32_e32 v123, v122, v106
	v_pk_mul_f32 v[72:73], v[124:125], v[72:73]
	v_sub_u32_e32 v124, 0, v123
	v_max_i32_e32 v124, v123, v124
	v_cvt_f32_u32_e32 v124, v124
	v_cmp_gt_i32_e32 vcc, 0, v123
	v_cvt_pk_bf16_f32 v69, v72, v73
	s_nop 0
	v_cndmask_b32_e32 v123, v108, v109, vcc
	v_mul_f32_e32 v125, v123, v124
	v_cmp_gt_f32_e32 vcc, s97, v125
	s_nop 1
	v_cndmask_b32_e32 v125, 0, v233, vcc
	v_fmac_f32_e32 v125, v123, v124
	v_exp_f32_e32 v123, v125
	v_cndmask_b32_e32 v124, 0, v236, vcc
	v_ldexp_f32 v124, v123, v124
	v_add_u32_e32 v123, v122, v107
	v_sub_u32_e32 v125, 0, v123
	v_max_i32_e32 v125, v123, v125
	v_cvt_f32_u32_e32 v125, v125
	v_cmp_gt_i32_e32 vcc, 0, v123
	s_nop 1
	v_cndmask_b32_e32 v123, v108, v109, vcc
	v_mul_f32_e32 v126, v123, v125
	v_cmp_gt_f32_e32 vcc, s97, v126
	s_nop 1
	v_cndmask_b32_e32 v126, 0, v233, vcc
	v_fmac_f32_e32 v126, v123, v125
	v_exp_f32_e32 v123, v126
	v_cndmask_b32_e32 v125, 0, v236, vcc
	v_ldexp_f32 v125, v123, v125
	v_add_u32_e32 v123, v122, v116
	v_pk_mul_f32 v[74:75], v[124:125], v[74:75]
	v_sub_u32_e32 v124, 0, v123
	v_max_i32_e32 v124, v123, v124
	v_cvt_f32_u32_e32 v124, v124
	v_cmp_gt_i32_e32 vcc, 0, v123
	v_cvt_pk_bf16_f32 v70, v74, v75
	s_nop 0
	v_cndmask_b32_e32 v123, v108, v109, vcc
	v_mul_f32_e32 v125, v123, v124
	v_cmp_gt_f32_e32 vcc, s97, v125
	s_nop 1
	v_cndmask_b32_e32 v125, 0, v233, vcc
	v_fmac_f32_e32 v125, v123, v124
	v_exp_f32_e32 v123, v125
	v_cndmask_b32_e32 v124, 0, v236, vcc
	v_ldexp_f32 v124, v123, v124
	v_add_u32_e32 v123, v122, v117
	v_sub_u32_e32 v125, 0, v123
	v_max_i32_e32 v125, v123, v125
	v_cvt_f32_u32_e32 v125, v125
	v_cmp_gt_i32_e32 vcc, 0, v123
	s_nop 1
	v_cndmask_b32_e32 v123, v108, v109, vcc
	v_mul_f32_e32 v126, v123, v125
	v_cmp_gt_f32_e32 vcc, s97, v126
	s_nop 1
	v_cndmask_b32_e32 v126, 0, v233, vcc
	v_fmac_f32_e32 v126, v123, v125
	v_exp_f32_e32 v123, v126
	v_cndmask_b32_e32 v125, 0, v236, vcc
	v_ldexp_f32 v125, v123, v125
	v_add_u32_e32 v123, v122, v118
	v_pk_mul_f32 v[76:77], v[124:125], v[76:77]
	v_sub_u32_e32 v124, 0, v123
	v_max_i32_e32 v124, v123, v124
	v_cvt_f32_u32_e32 v124, v124
	v_cmp_gt_i32_e32 vcc, 0, v123
	v_cvt_pk_bf16_f32 v71, v76, v77
	ds_read_b64_tr_b16 v[74:75], v115 offset:16384
	ds_read_b64_tr_b16 v[76:77], v115 offset:18432
	v_cndmask_b32_e32 v123, v108, v109, vcc
	v_mul_f32_e32 v125, v123, v124
	v_cmp_gt_f32_e32 vcc, s97, v125
	s_waitcnt lgkmcnt(0)
	v_mfma_f32_32x32x16_bf16 v[2:17], v[74:77], v[66:69], v[2:17]
	v_cndmask_b32_e32 v125, 0, v233, vcc
	v_fmac_f32_e32 v125, v123, v124
	v_exp_f32_e32 v123, v125
	v_cndmask_b32_e32 v124, 0, v236, vcc
	ds_read_b64_tr_b16 v[74:75], v115 offset:20480
	ds_read_b64_tr_b16 v[76:77], v115 offset:22528
	v_ldexp_f32 v124, v123, v124
	v_add_u32_e32 v123, v122, v119
	v_sub_u32_e32 v125, 0, v123
	v_max_i32_e32 v125, v123, v125
	v_cvt_f32_u32_e32 v125, v125
	v_cmp_gt_i32_e32 vcc, 0, v123
	s_nop 1
	v_cndmask_b32_e32 v123, v108, v109, vcc
	v_mul_f32_e32 v126, v123, v125
	v_cmp_gt_f32_e32 vcc, s97, v126
	s_nop 1
	v_cndmask_b32_e32 v126, 0, v233, vcc
	v_fmac_f32_e32 v126, v123, v125
	v_exp_f32_e32 v123, v126
	v_cndmask_b32_e32 v125, 0, v236, vcc
	v_ldexp_f32 v125, v123, v125
	v_add_u32_e32 v123, v122, v121
	v_pk_mul_f32 v[78:79], v[124:125], v[78:79]
	v_sub_u32_e32 v124, 0, v123
	v_max_i32_e32 v124, v123, v124
	v_cvt_f32_u32_e32 v124, v124
	v_cmp_gt_i32_e32 vcc, 0, v123
	v_add_u32_e32 v122, v122, v120
	v_cvt_pk_bf16_f32 v72, v78, v79
	v_cndmask_b32_e32 v123, v108, v109, vcc
	v_mul_f32_e32 v125, v123, v124
	v_cmp_gt_f32_e32 vcc, s97, v125
	s_nop 1
	v_cndmask_b32_e32 v125, 0, v233, vcc
	v_fmac_f32_e32 v125, v123, v124
	v_exp_f32_e32 v123, v125
	v_cndmask_b32_e32 v124, 0, v236, vcc
	v_cmp_gt_i32_e32 vcc, 0, v122
	v_ldexp_f32 v124, v123, v124
	v_sub_u32_e32 v123, 0, v122
	v_max_i32_e32 v123, v122, v123
	v_cvt_f32_u32_e32 v123, v123
	v_cndmask_b32_e32 v122, v108, v109, vcc
	v_mul_f32_e32 v125, v122, v123
	v_cmp_gt_f32_e32 vcc, s97, v125
	s_nop 1
	v_cndmask_b32_e32 v125, 0, v233, vcc
	v_fmac_f32_e32 v125, v122, v123
	v_exp_f32_e32 v122, v125
	v_cndmask_b32_e32 v123, 0, v236, vcc
	v_ldexp_f32 v125, v122, v123
	v_pk_mul_f32 v[80:81], v[124:125], v[80:81]
	s_nop 0
	v_cvt_pk_bf16_f32 v73, v80, v81
	s_waitcnt lgkmcnt(0)
	s_nop 0
	v_mfma_f32_32x32x16_bf16 v[2:17], v[74:77], v[70:73], v[2:17]
	ds_read_b64_tr_b16 v[74:75], v115 offset:16448
	ds_read_b64_tr_b16 v[76:77], v115 offset:18496
	s_waitcnt lgkmcnt(0)
	v_mfma_f32_32x32x16_bf16 v[18:33], v[74:77], v[66:69], v[18:33]
	ds_read_b64_tr_b16 v[74:75], v115 offset:20544
	ds_read_b64_tr_b16 v[76:77], v115 offset:22592
	s_waitcnt lgkmcnt(0)
	v_mfma_f32_32x32x16_bf16 v[18:33], v[74:77], v[70:73], v[18:33]
	ds_read_b64_tr_b16 v[74:75], v115 offset:16512
	ds_read_b64_tr_b16 v[76:77], v115 offset:18560
	s_waitcnt lgkmcnt(0)
	v_mfma_f32_32x32x16_bf16 v[34:49], v[74:77], v[66:69], v[34:49]
	ds_read_b64_tr_b16 v[74:75], v115 offset:20608
	ds_read_b64_tr_b16 v[76:77], v115 offset:22656
	s_waitcnt lgkmcnt(0)
	v_mfma_f32_32x32x16_bf16 v[34:49], v[74:77], v[70:73], v[34:49]
	ds_read_b64_tr_b16 v[74:75], v115 offset:16576
	ds_read_b64_tr_b16 v[76:77], v115 offset:18624
	s_waitcnt lgkmcnt(0)
	v_mfma_f32_32x32x16_bf16 v[50:65], v[74:77], v[66:69], v[50:65]
	ds_read_b64_tr_b16 v[66:67], v115 offset:20672
	ds_read_b64_tr_b16 v[68:69], v115 offset:22720
	s_waitcnt lgkmcnt(0)
	v_mfma_f32_32x32x16_bf16 v[50:65], v[66:69], v[70:73], v[50:65]
	s_nop 1
	s_waitcnt vmcnt(3)
	v_mfma_f32_32x32x16_bf16 v[66:81], v[216:219], v[94:97], 0
	s_waitcnt vmcnt(2)
	v_mfma_f32_32x32x16_bf16 v[66:81], v[220:223], v[90:93], v[66:81]
	v_add_u32_e32 v122, 0xffffffa0, v155
	v_mad_i32_i24 v98, v154, -4, v122
	v_sub_u32_e32 v99, 0, v98
	v_max_i32_e32 v99, v98, v99
	v_cvt_f32_u32_e32 v99, v99
	v_cmp_gt_i32_e32 vcc, 0, v98
	v_add_u32_e32 v0, v122, v0
	s_waitcnt vmcnt(1)
	v_mfma_f32_32x32x16_bf16 v[66:81], v[134:137], v[86:89], v[66:81]
	v_cndmask_b32_e32 v98, v108, v109, vcc
	v_mul_f32_e32 v123, v98, v99
	v_cmp_gt_f32_e32 vcc, s97, v123
	s_nop 1
	v_cndmask_b32_e32 v123, 0, v233, vcc
	v_fmac_f32_e32 v123, v98, v99
	v_exp_f32_e32 v98, v123
	v_cndmask_b32_e32 v99, 0, v236, vcc
	v_cmp_gt_i32_e32 vcc, 0, v0
	s_waitcnt vmcnt(0)
	v_mfma_f32_32x32x16_bf16 v[66:81], v[138:141], v[82:85], v[66:81]
	v_ldexp_f32 v98, v98, v99
	v_sub_u32_e32 v99, 0, v0
	v_max_i32_e32 v99, v0, v99
	v_cvt_f32_u32_e32 v99, v99
	v_cndmask_b32_e32 v0, v108, v109, vcc
	v_mul_f32_e32 v123, v0, v99
	v_cmp_gt_f32_e32 vcc, s97, v123
	s_nop 1
	v_cndmask_b32_e32 v123, 0, v233, vcc
	v_fmac_f32_e32 v123, v0, v99
	v_exp_f32_e32 v0, v123
	v_cndmask_b32_e32 v99, 0, v236, vcc
	v_ldexp_f32 v99, v0, v99
	v_add_u32_e32 v0, v122, v100
	v_sub_u32_e32 v100, 0, v0
	v_max_i32_e32 v100, v0, v100
	v_cvt_f32_u32_e32 v100, v100
	v_cmp_gt_i32_e32 vcc, 0, v0
	v_pk_mul_f32 v[66:67], v[98:99], v[66:67]
	s_nop 0
	v_cndmask_b32_e32 v0, v108, v109, vcc
	v_mul_f32_e32 v123, v0, v100
	v_cmp_gt_f32_e32 vcc, s97, v123
	v_cvt_pk_bf16_f32 v66, v66, v67
	s_nop 0
	v_cndmask_b32_e32 v123, 0, v233, vcc
	v_fmac_f32_e32 v123, v0, v100
	v_exp_f32_e32 v0, v123
	v_cndmask_b32_e32 v100, 0, v236, vcc
	v_ldexp_f32 v100, v0, v100
	v_add_u32_e32 v0, v122, v101
	v_sub_u32_e32 v101, 0, v0
	v_max_i32_e32 v101, v0, v101
	v_cvt_f32_u32_e32 v101, v101
	v_cmp_gt_i32_e32 vcc, 0, v0
	s_nop 1
	v_cndmask_b32_e32 v0, v108, v109, vcc
	v_mul_f32_e32 v123, v0, v101
	v_cmp_gt_f32_e32 vcc, s97, v123
	s_nop 1
	v_cndmask_b32_e32 v123, 0, v233, vcc
	v_fmac_f32_e32 v123, v0, v101
	v_exp_f32_e32 v0, v123
	v_cndmask_b32_e32 v101, 0, v236, vcc
	v_ldexp_f32 v101, v0, v101
	v_add_u32_e32 v0, v122, v102
	v_sub_u32_e32 v102, 0, v0
	v_max_i32_e32 v102, v0, v102
	v_cvt_f32_u32_e32 v102, v102
	v_cmp_gt_i32_e32 vcc, 0, v0
	v_pk_mul_f32 v[68:69], v[100:101], v[68:69]
	s_nop 0
	v_cndmask_b32_e32 v0, v108, v109, vcc
	v_mul_f32_e32 v123, v0, v102
	v_cmp_gt_f32_e32 vcc, s97, v123
	v_cvt_pk_bf16_f32 v67, v68, v69
	s_nop 0
	v_cndmask_b32_e32 v123, 0, v233, vcc
	v_fmac_f32_e32 v123, v0, v102
	v_exp_f32_e32 v0, v123
	v_cndmask_b32_e32 v102, 0, v236, vcc
	v_ldexp_f32 v102, v0, v102
	v_add_u32_e32 v0, v122, v103
	v_sub_u32_e32 v103, 0, v0
	v_max_i32_e32 v103, v0, v103
	v_cvt_f32_u32_e32 v103, v103
	v_cmp_gt_i32_e32 vcc, 0, v0
	s_nop 1
	v_cndmask_b32_e32 v0, v108, v109, vcc
	v_mul_f32_e32 v123, v0, v103
	v_cmp_gt_f32_e32 vcc, s97, v123
	s_nop 1
	v_cndmask_b32_e32 v123, 0, v233, vcc
	v_fmac_f32_e32 v123, v0, v103
	v_exp_f32_e32 v0, v123
	v_cndmask_b32_e32 v103, 0, v236, vcc
	v_ldexp_f32 v103, v0, v103
	v_add_u32_e32 v0, v122, v104
	v_sub_u32_e32 v104, 0, v0
	v_max_i32_e32 v104, v0, v104
	v_cvt_f32_u32_e32 v104, v104
	v_cmp_gt_i32_e32 vcc, 0, v0
	v_pk_mul_f32 v[70:71], v[102:103], v[70:71]
	s_nop 0
	v_cndmask_b32_e32 v0, v108, v109, vcc
	v_mul_f32_e32 v123, v0, v104
	v_cmp_gt_f32_e32 vcc, s97, v123
	v_cvt_pk_bf16_f32 v68, v70, v71
	s_nop 0
	v_cndmask_b32_e32 v123, 0, v233, vcc
	v_fmac_f32_e32 v123, v0, v104
	v_exp_f32_e32 v0, v123
	v_cndmask_b32_e32 v104, 0, v236, vcc
	v_ldexp_f32 v104, v0, v104
	v_add_u32_e32 v0, v122, v105
	v_sub_u32_e32 v105, 0, v0
	v_max_i32_e32 v105, v0, v105
	v_cvt_f32_u32_e32 v105, v105
	v_cmp_gt_i32_e32 vcc, 0, v0
	s_nop 1
	v_cndmask_b32_e32 v0, v108, v109, vcc
	v_mul_f32_e32 v123, v0, v105
	v_cmp_gt_f32_e32 vcc, s97, v123
	s_nop 1
	v_cndmask_b32_e32 v123, 0, v233, vcc
	v_fmac_f32_e32 v123, v0, v105
	v_exp_f32_e32 v0, v123
	v_cndmask_b32_e32 v105, 0, v236, vcc
	v_ldexp_f32 v105, v0, v105
	v_add_u32_e32 v0, v122, v106
	v_sub_u32_e32 v106, 0, v0
	v_max_i32_e32 v106, v0, v106
	v_cvt_f32_u32_e32 v106, v106
	v_cmp_gt_i32_e32 vcc, 0, v0
	v_pk_mul_f32 v[72:73], v[104:105], v[72:73]
	s_nop 0
	v_cndmask_b32_e32 v0, v108, v109, vcc
	v_mul_f32_e32 v123, v0, v106
	v_cmp_gt_f32_e32 vcc, s97, v123
	v_cvt_pk_bf16_f32 v69, v72, v73
	s_nop 0
	v_cndmask_b32_e32 v123, 0, v233, vcc
	v_fmac_f32_e32 v123, v0, v106
	v_exp_f32_e32 v0, v123
	v_cndmask_b32_e32 v106, 0, v236, vcc
	v_ldexp_f32 v106, v0, v106
	v_add_u32_e32 v0, v122, v107
	v_sub_u32_e32 v107, 0, v0
	v_max_i32_e32 v107, v0, v107
	v_cvt_f32_u32_e32 v107, v107
	v_cmp_gt_i32_e32 vcc, 0, v0
	s_nop 1
	v_cndmask_b32_e32 v0, v108, v109, vcc
	v_mul_f32_e32 v123, v0, v107
	v_cmp_gt_f32_e32 vcc, s97, v123
	s_nop 1
	v_cndmask_b32_e32 v123, 0, v233, vcc
	v_fmac_f32_e32 v123, v0, v107
	v_exp_f32_e32 v0, v123
	v_cndmask_b32_e32 v107, 0, v236, vcc
	v_ldexp_f32 v107, v0, v107
	v_add_u32_e32 v0, v122, v116
	v_sub_u32_e32 v116, 0, v0
	v_max_i32_e32 v116, v0, v116
	v_cvt_f32_u32_e32 v116, v116
	v_cmp_gt_i32_e32 vcc, 0, v0
	v_pk_mul_f32 v[74:75], v[106:107], v[74:75]
	s_nop 0
	v_cndmask_b32_e32 v0, v108, v109, vcc
	v_mul_f32_e32 v123, v0, v116
	v_cmp_gt_f32_e32 vcc, s97, v123
	v_cvt_pk_bf16_f32 v70, v74, v75
	s_nop 0
	v_cndmask_b32_e32 v123, 0, v233, vcc
	v_fmac_f32_e32 v123, v0, v116
	v_exp_f32_e32 v0, v123
	v_cndmask_b32_e32 v116, 0, v236, vcc
	v_ldexp_f32 v116, v0, v116
	v_add_u32_e32 v0, v122, v117
	v_sub_u32_e32 v117, 0, v0
	v_max_i32_e32 v117, v0, v117
	v_cvt_f32_u32_e32 v117, v117
	v_cmp_gt_i32_e32 vcc, 0, v0
	s_nop 1
	v_cndmask_b32_e32 v0, v108, v109, vcc
	v_mul_f32_e32 v123, v0, v117
	v_cmp_gt_f32_e32 vcc, s97, v123
	s_nop 1
	v_cndmask_b32_e32 v123, 0, v233, vcc
	v_fmac_f32_e32 v123, v0, v117
	v_exp_f32_e32 v0, v123
	v_cndmask_b32_e32 v117, 0, v236, vcc
	v_ldexp_f32 v117, v0, v117
	v_add_u32_e32 v0, v122, v118
	v_sub_u32_e32 v118, 0, v0
	v_max_i32_e32 v118, v0, v118
	v_cvt_f32_u32_e32 v118, v118
	v_cmp_gt_i32_e32 vcc, 0, v0
	v_pk_mul_f32 v[76:77], v[116:117], v[76:77]
	s_nop 0
	v_cndmask_b32_e32 v0, v108, v109, vcc
	v_mul_f32_e32 v123, v0, v118
	v_cmp_gt_f32_e32 vcc, s97, v123
	v_cvt_pk_bf16_f32 v71, v76, v77
	ds_read_b64_tr_b16 v[74:75], v115 offset:24576
	ds_read_b64_tr_b16 v[76:77], v115 offset:26624
	v_cndmask_b32_e32 v123, 0, v233, vcc
	v_fmac_f32_e32 v123, v0, v118
	v_exp_f32_e32 v0, v123
	v_cndmask_b32_e32 v118, 0, v236, vcc
	s_waitcnt lgkmcnt(0)
	v_mfma_f32_32x32x16_bf16 v[2:17], v[74:77], v[66:69], v[2:17]
	ds_read_b64_tr_b16 v[74:75], v115 offset:28672
	ds_read_b64_tr_b16 v[76:77], v115 offset:30720
	v_ldexp_f32 v118, v0, v118
	v_add_u32_e32 v0, v122, v119
	v_sub_u32_e32 v119, 0, v0
	v_max_i32_e32 v119, v0, v119
	v_cvt_f32_u32_e32 v119, v119
	v_cmp_gt_i32_e32 vcc, 0, v0
	s_nop 1
	v_cndmask_b32_e32 v0, v108, v109, vcc
	v_mul_f32_e32 v123, v0, v119
	v_cmp_gt_f32_e32 vcc, s97, v123
	s_nop 1
	v_cndmask_b32_e32 v123, 0, v233, vcc
	v_fmac_f32_e32 v123, v0, v119
	v_exp_f32_e32 v0, v123
	v_cndmask_b32_e32 v119, 0, v236, vcc
	v_ldexp_f32 v119, v0, v119
	v_add_u32_e32 v0, v122, v121
	v_sub_u32_e32 v121, 0, v0
	v_max_i32_e32 v121, v0, v121
	v_cvt_f32_u32_e32 v121, v121
	v_cmp_gt_i32_e32 vcc, 0, v0
	v_pk_mul_f32 v[78:79], v[118:119], v[78:79]
	s_nop 0
	v_cndmask_b32_e32 v0, v108, v109, vcc
	v_mul_f32_e32 v123, v0, v121
	v_cmp_gt_f32_e32 vcc, s97, v123
	v_cvt_pk_bf16_f32 v72, v78, v79
	s_nop 0
	v_cndmask_b32_e32 v123, 0, v233, vcc
	v_fmac_f32_e32 v123, v0, v121
	v_exp_f32_e32 v0, v123
	v_cndmask_b32_e32 v121, 0, v236, vcc
	v_ldexp_f32 v124, v0, v121
	v_add_u32_e32 v0, v122, v120
	v_sub_u32_e32 v120, 0, v0
	v_max_i32_e32 v120, v0, v120
	v_cvt_f32_u32_e32 v120, v120
	v_cmp_gt_i32_e32 vcc, 0, v0
	s_nop 1
	v_cndmask_b32_e32 v0, v108, v109, vcc
	v_mul_f32_e32 v121, v0, v120
	v_cmp_gt_f32_e32 vcc, s97, v121
	s_nop 1
	v_cndmask_b32_e32 v121, 0, v233, vcc
	v_fmac_f32_e32 v121, v0, v120
	v_exp_f32_e32 v0, v121
	v_cndmask_b32_e32 v120, 0, v236, vcc
	v_ldexp_f32 v125, v0, v120
	v_pk_mul_f32 v[80:81], v[124:125], v[80:81]
	v_sub_u32_e32 v0, 0x80, v155
	v_cvt_pk_bf16_f32 v73, v80, v81
	v_cvt_f32_ubyte0_e32 v0, v0
	s_waitcnt lgkmcnt(0)
	v_mfma_f32_32x32x16_bf16 v[2:17], v[74:77], v[70:73], v[2:17]
	ds_read_b64_tr_b16 v[74:75], v115 offset:24640
	ds_read_b64_tr_b16 v[76:77], v115 offset:26688
	s_waitcnt lgkmcnt(0)
	v_mfma_f32_32x32x16_bf16 v[18:33], v[74:77], v[66:69], v[18:33]
	ds_read_b64_tr_b16 v[74:75], v115 offset:28736
	ds_read_b64_tr_b16 v[76:77], v115 offset:30784
	s_waitcnt lgkmcnt(0)
	v_mfma_f32_32x32x16_bf16 v[18:33], v[74:77], v[70:73], v[18:33]
	ds_read_b64_tr_b16 v[74:75], v115 offset:24704
	ds_read_b64_tr_b16 v[76:77], v115 offset:26752
	s_waitcnt lgkmcnt(0)
	v_mfma_f32_32x32x16_bf16 v[34:49], v[74:77], v[66:69], v[34:49]
	ds_read_b64_tr_b16 v[74:75], v115 offset:28800
	ds_read_b64_tr_b16 v[76:77], v115 offset:30848
	s_waitcnt lgkmcnt(0)
	v_mfma_f32_32x32x16_bf16 v[34:49], v[74:77], v[70:73], v[34:49]
	ds_read_b64_tr_b16 v[74:75], v115 offset:24768
	ds_read_b64_tr_b16 v[76:77], v115 offset:26816
	s_waitcnt lgkmcnt(0)
	v_mfma_f32_32x32x16_bf16 v[50:65], v[74:77], v[66:69], v[50:65]
	ds_read_b64_tr_b16 v[66:67], v115 offset:28864
	ds_read_b64_tr_b16 v[68:69], v115 offset:30912
	s_waitcnt lgkmcnt(0)
	v_mfma_f32_32x32x16_bf16 v[50:65], v[66:69], v[70:73], v[50:65]
	v_mul_f32_e32 v68, v109, v0
	v_cmp_gt_f32_e32 vcc, s97, v68
	v_or_b32_e32 v66, v112, v110
	v_add3_u32 v67, s88, v113, v114
	v_cndmask_b32_e32 v68, 0, v233, vcc
	v_fmac_f32_e32 v68, v109, v0
	v_exp_f32_e32 v0, v68
	v_cndmask_b32_e32 v68, 0, v236, vcc
	v_lshlrev_b32_e32 v66, 8, v66
	v_add3_u32 v147, v67, v111, v66
	v_ldexp_f32 v0, v0, v68
	v_add_u32_e32 v68, 1, v155
	v_cvt_f32_ubyte0_e32 v68, v68
	v_mul_f32_e32 v69, v108, v68
	v_cmp_gt_f32_e32 vcc, s97, v69
	s_nop 1
	v_cndmask_b32_e32 v69, 0, v233, vcc
	v_fmac_f32_e32 v69, v108, v68
	v_exp_f32_e32 v68, v69
	v_cndmask_b32_e32 v69, 0, v236, vcc
	v_ldexp_f32 v148, v68, v69
	v_pk_mul_f32 v[152:153], v[148:149], v[150:151] op_sel_hi:[0,1]
	v_cvt_pk_bf16_f32 v94, v152, v153
	v_lshlrev_b32_e32 v152, 16, v95
	v_and_b32_e32 v153, 0xffff0000, v95
	v_pk_mul_f32 v[158:159], v[148:149], v[152:153] op_sel_hi:[0,1]
	v_cvt_pk_bf16_f32 v95, v158, v159
	v_lshlrev_b32_e32 v158, 16, v96
	v_and_b32_e32 v159, 0xffff0000, v96
	v_pk_mul_f32 v[160:161], v[148:149], v[158:159] op_sel_hi:[0,1]
	v_cvt_pk_bf16_f32 v96, v160, v161
	v_lshlrev_b32_e32 v160, 16, v97
	v_and_b32_e32 v161, 0xffff0000, v97
	v_pk_mul_f32 v[162:163], v[148:149], v[160:161] op_sel_hi:[0,1]
	v_pk_mul_f32 v[150:151], v[0:1], v[150:151] op_sel_hi:[0,1]
	v_cvt_pk_bf16_f32 v97, v162, v163
	ds_read_b64_tr_b16 v[106:107], v147
	ds_read_b64_tr_b16 v[108:109], v147 offset:1024
	ds_read_b64_tr_b16 v[114:115], v147 offset:64
	ds_read_b64_tr_b16 v[116:117], v147 offset:1088
	ds_read_b64_tr_b16 v[110:111], v147 offset:128
	ds_read_b64_tr_b16 v[112:113], v147 offset:1152
	ds_read_b64_tr_b16 v[98:99], v147 offset:192
	ds_read_b64_tr_b16 v[100:101], v147 offset:1216
	ds_read_b64_tr_b16 v[142:143], v147 offset:2048
	ds_read_b64_tr_b16 v[144:145], v147 offset:3072
	ds_read_b64_tr_b16 v[138:139], v147 offset:2112
	ds_read_b64_tr_b16 v[140:141], v147 offset:3136
	ds_read_b64_tr_b16 v[134:135], v147 offset:2176
	ds_read_b64_tr_b16 v[136:137], v147 offset:3200
	ds_read_b64_tr_b16 v[130:131], v147 offset:2240
	ds_read_b64_tr_b16 v[132:133], v147 offset:3264
	ds_read_b64_tr_b16 v[126:127], v147 offset:4096
	ds_read_b64_tr_b16 v[128:129], v147 offset:5120
	ds_read_b64_tr_b16 v[122:123], v147 offset:4160
	ds_read_b64_tr_b16 v[124:125], v147 offset:5184
	ds_read_b64_tr_b16 v[118:119], v147 offset:4224
	ds_read_b64_tr_b16 v[120:121], v147 offset:5248
	ds_read_b64_tr_b16 v[102:103], v147 offset:4288
	ds_read_b64_tr_b16 v[104:105], v147 offset:5312
	ds_read_b64_tr_b16 v[78:79], v147 offset:6144
	ds_read_b64_tr_b16 v[80:81], v147 offset:7168
	ds_read_b64_tr_b16 v[74:75], v147 offset:6208
	ds_read_b64_tr_b16 v[76:77], v147 offset:7232
	ds_read_b64_tr_b16 v[70:71], v147 offset:6272
	ds_read_b64_tr_b16 v[72:73], v147 offset:7296
	ds_read_b64_tr_b16 v[66:67], v147 offset:6336
	ds_read_b64_tr_b16 v[68:69], v147 offset:7360
	v_pk_mul_f32 v[152:153], v[0:1], v[152:153] op_sel_hi:[0,1]
	s_waitcnt lgkmcnt(14)
	v_mfma_f32_32x32x16_bf16 v[2:17], v[106:109], v[94:97], v[2:17]
	v_mul_f32_e64 v158, v0, v158
	v_mul_f32_e64 v159, v0, v159
	v_mfma_f32_32x32x16_bf16 v[18:33], v[114:117], v[94:97], v[18:33]
	v_mfma_f32_32x32x16_bf16 v[34:49], v[110:113], v[94:97], v[34:49]
	v_mfma_f32_32x32x16_bf16 v[50:65], v[98:101], v[94:97], v[50:65]
	v_cvt_pk_bf16_f32 v94, v150, v151
	v_lshlrev_b32_e32 v150, 16, v90
	v_and_b32_e32 v151, 0xffff0000, v90
	v_cvt_pk_bf16_f32 v95, v152, v153
	v_mul_f32_e64 v152, v148, v150
	v_mul_f32_e64 v153, v148, v151
	v_cvt_pk_bf16_f32 v90, v152, v153
	v_lshlrev_b32_e32 v152, 16, v91
	v_and_b32_e32 v153, 0xffff0000, v91
	v_cvt_pk_bf16_f32 v96, v158, v159
	v_pk_mul_f32 v[158:159], v[148:149], v[152:153] op_sel_hi:[0,1]
	v_cvt_pk_bf16_f32 v91, v158, v159
	v_lshlrev_b32_e32 v158, 16, v92
	v_and_b32_e32 v159, 0xffff0000, v92
	v_pk_mul_f32 v[98:99], v[0:1], v[160:161] op_sel_hi:[0,1]
	v_pk_mul_f32 v[160:161], v[148:149], v[158:159] op_sel_hi:[0,1]
	v_cvt_pk_bf16_f32 v92, v160, v161
	v_lshlrev_b32_e32 v160, 16, v93
	v_and_b32_e32 v161, 0xffff0000, v93
	v_pk_mul_f32 v[162:163], v[148:149], v[160:161] op_sel_hi:[0,1]
	v_pk_mul_f32 v[150:151], v[0:1], v[150:151] op_sel_hi:[0,1]
	v_cvt_pk_bf16_f32 v93, v162, v163
	v_pk_mul_f32 v[152:153], v[0:1], v[152:153] op_sel_hi:[0,1]
	v_pk_mul_f32 v[158:159], v[0:1], v[158:159] op_sel_hi:[0,1]
	v_mfma_f32_32x32x16_bf16 v[2:17], v[142:145], v[90:93], v[2:17]
	v_cvt_pk_bf16_f32 v97, v98, v99
	ds_read_b64_tr_b16 v[114:115], v147 offset:16384
	ds_read_b64_tr_b16 v[116:117], v147 offset:17408
	ds_read_b64_tr_b16 v[110:111], v147 offset:16448
	ds_read_b64_tr_b16 v[112:113], v147 offset:17472
	ds_read_b64_tr_b16 v[106:107], v147 offset:16512
	ds_read_b64_tr_b16 v[108:109], v147 offset:17536
	ds_read_b64_tr_b16 v[98:99], v147 offset:16576
	ds_read_b64_tr_b16 v[100:101], v147 offset:17600
	v_mfma_f32_32x32x16_bf16 v[18:33], v[138:141], v[90:93], v[18:33]
	v_mfma_f32_32x32x16_bf16 v[34:49], v[134:137], v[90:93], v[34:49]
	v_mfma_f32_32x32x16_bf16 v[50:65], v[130:133], v[90:93], v[50:65]
	v_cvt_pk_bf16_f32 v90, v150, v151
	v_lshlrev_b32_e32 v150, 16, v86
	v_and_b32_e32 v151, 0xffff0000, v86
	v_cvt_pk_bf16_f32 v91, v152, v153
	v_mul_f32_e64 v152, v148, v150
	v_mul_f32_e64 v153, v148, v151
	v_cvt_pk_bf16_f32 v86, v152, v153
	v_lshlrev_b32_e32 v152, 16, v87
	v_and_b32_e32 v153, 0xffff0000, v87
	v_cvt_pk_bf16_f32 v92, v158, v159
	v_pk_mul_f32 v[158:159], v[148:149], v[152:153] op_sel_hi:[0,1]
	v_cvt_pk_bf16_f32 v87, v158, v159
	v_lshlrev_b32_e32 v158, 16, v88
	v_and_b32_e32 v159, 0xffff0000, v88
	v_pk_mul_f32 v[130:131], v[0:1], v[160:161] op_sel_hi:[0,1]
	v_pk_mul_f32 v[160:161], v[148:149], v[158:159] op_sel_hi:[0,1]
	v_cvt_pk_bf16_f32 v88, v160, v161
	v_lshlrev_b32_e32 v160, 16, v89
	v_and_b32_e32 v161, 0xffff0000, v89
	v_pk_mul_f32 v[162:163], v[148:149], v[160:161] op_sel_hi:[0,1]
	v_cvt_pk_bf16_f32 v89, v162, v163
	v_pk_mul_f32 v[150:151], v[0:1], v[150:151] op_sel_hi:[0,1]
	v_pk_mul_f32 v[152:153], v[0:1], v[152:153] op_sel_hi:[0,1]
	v_mfma_f32_32x32x16_bf16 v[2:17], v[126:129], v[86:89], v[2:17]
	v_mul_f32_e64 v158, v0, v158
	v_mul_f32_e64 v159, v0, v159
	v_cvt_pk_bf16_f32 v93, v130, v131
	ds_read_b64_tr_b16 v[142:143], v147 offset:18432
	ds_read_b64_tr_b16 v[144:145], v147 offset:19456
	ds_read_b64_tr_b16 v[138:139], v147 offset:18496
	ds_read_b64_tr_b16 v[140:141], v147 offset:19520
	ds_read_b64_tr_b16 v[134:135], v147 offset:18560
	ds_read_b64_tr_b16 v[136:137], v147 offset:19584
	ds_read_b64_tr_b16 v[130:131], v147 offset:18624
	ds_read_b64_tr_b16 v[132:133], v147 offset:19648
	s_waitcnt lgkmcnt(14)
	v_mfma_f32_32x32x16_bf16 v[18:33], v[122:125], v[86:89], v[18:33]
	v_mfma_f32_32x32x16_bf16 v[34:49], v[118:121], v[86:89], v[34:49]
	v_mfma_f32_32x32x16_bf16 v[50:65], v[102:105], v[86:89], v[50:65]
	v_cvt_pk_bf16_f32 v86, v150, v151
	v_lshlrev_b32_e32 v150, 16, v82
	v_and_b32_e32 v151, 0xffff0000, v82
	v_cvt_pk_bf16_f32 v87, v152, v153
	v_mul_f32_e64 v152, v148, v150
	v_mul_f32_e64 v153, v148, v151
	v_lshlrev_b32_e32 v82, 16, v83
	v_and_b32_e32 v83, 0xffff0000, v83
	v_cvt_pk_bf16_f32 v88, v158, v159
	v_cvt_pk_bf16_f32 v158, v152, v153
	v_pk_mul_f32 v[152:153], v[148:149], v[82:83] op_sel_hi:[0,1]
	v_cvt_pk_bf16_f32 v159, v152, v153
	v_lshlrev_b32_e32 v152, 16, v84
	v_and_b32_e32 v153, 0xffff0000, v84
	v_lshlrev_b32_e32 v84, 16, v85
	v_and_b32_e32 v85, 0xffff0000, v85
	v_pk_mul_f32 v[102:103], v[0:1], v[160:161] op_sel_hi:[0,1]
	v_pk_mul_f32 v[160:161], v[148:149], v[152:153] op_sel_hi:[0,1]
	v_pk_mul_f32 v[162:163], v[148:149], v[84:85] op_sel_hi:[0,1]
	v_cvt_pk_bf16_f32 v160, v160, v161
	v_cvt_pk_bf16_f32 v161, v162, v163
	v_cvt_pk_bf16_f32 v89, v102, v103
	ds_read_b64_tr_b16 v[126:127], v147 offset:20480
	ds_read_b64_tr_b16 v[128:129], v147 offset:21504
	ds_read_b64_tr_b16 v[122:123], v147 offset:20544
	ds_read_b64_tr_b16 v[124:125], v147 offset:21568
	ds_read_b64_tr_b16 v[118:119], v147 offset:20608
	ds_read_b64_tr_b16 v[120:121], v147 offset:21632
	ds_read_b64_tr_b16 v[102:103], v147 offset:20672
	ds_read_b64_tr_b16 v[104:105], v147 offset:21696
	v_mfma_f32_32x32x16_bf16 v[2:17], v[78:81], v[158:161], v[2:17]
	v_mul_f32_e64 v150, v0, v150
	v_mul_f32_e64 v151, v0, v151
	v_mul_f32_e64 v82, v0, v82
	v_mul_f32_e64 v83, v0, v83
	v_mul_f32_e64 v152, v0, v152
	v_mul_f32_e64 v153, v0, v153
	v_mfma_f32_32x32x16_bf16 v[2:17], v[114:117], v[94:97], v[2:17]
	v_mfma_f32_32x32x16_bf16 v[18:33], v[74:77], v[158:161], v[18:33]
	s_waitcnt lgkmcnt(14)
	v_mfma_f32_32x32x16_bf16 v[2:17], v[142:145], v[90:93], v[2:17]
	v_mfma_f32_32x32x16_bf16 v[18:33], v[110:113], v[94:97], v[18:33]
	s_waitcnt lgkmcnt(6)
	v_mfma_f32_32x32x16_bf16 v[2:17], v[126:129], v[86:89], v[2:17]
	v_mfma_f32_32x32x16_bf16 v[34:49], v[70:73], v[158:161], v[34:49]
	v_mul_f32_e64 v70, v0, v84
	v_mul_f32_e64 v71, v0, v85
	v_mfma_f32_32x32x16_bf16 v[50:65], v[66:69], v[158:161], v[50:65]
	v_cvt_pk_bf16_f32 v69, v70, v71
	ds_read_b64_tr_b16 v[70:71], v147 offset:22528
	ds_read_b64_tr_b16 v[72:73], v147 offset:23552
	v_cvt_pk_bf16_f32 v66, v150, v151
	v_cvt_pk_bf16_f32 v67, v82, v83
	v_cvt_pk_bf16_f32 v68, v152, v153
	v_mfma_f32_32x32x16_bf16 v[18:33], v[138:141], v[90:93], v[18:33]
	s_waitcnt lgkmcnt(0)
	v_mfma_f32_32x32x16_bf16 v[2:17], v[70:73], v[66:69], v[2:17]
	ds_read_b64_tr_b16 v[70:71], v147 offset:22592
	ds_read_b64_tr_b16 v[72:73], v147 offset:23616
	v_mfma_f32_32x32x16_bf16 v[34:49], v[106:109], v[94:97], v[34:49]
	s_nop 8
	v_add_f32_e32 v0, 0, v2
	v_add_f32_e32 v0, v3, v0
	v_add_f32_e32 v0, v4, v0
	v_add_f32_e32 v0, v5, v0
	v_add_f32_e32 v0, v6, v0
	v_add_f32_e32 v0, v7, v0
	v_add_f32_e32 v0, v8, v0
	v_mfma_f32_32x32x16_bf16 v[18:33], v[122:125], v[86:89], v[18:33]
	v_add_f32_e32 v0, v9, v0
	v_add_f32_e32 v0, v10, v0
	v_add_f32_e32 v0, v11, v0
	v_add_f32_e32 v0, v12, v0
	v_add_f32_e32 v0, v13, v0
	v_add_f32_e32 v0, v14, v0
	v_add_f32_e32 v0, v15, v0
	v_mfma_f32_32x32x16_bf16 v[34:49], v[134:137], v[90:93], v[34:49]
	v_add_f32_e32 v0, v16, v0
	v_add_f32_e32 v0, v17, v0
	s_waitcnt lgkmcnt(0)
	v_mfma_f32_32x32x16_bf16 v[18:33], v[70:73], v[66:69], v[18:33]
	ds_read_b64_tr_b16 v[70:71], v147 offset:22656
	ds_read_b64_tr_b16 v[72:73], v147 offset:23680
	v_mfma_f32_32x32x16_bf16 v[50:65], v[98:101], v[94:97], v[50:65]
	s_nop 8
	v_add_f32_e32 v0, v18, v0
	v_add_f32_e32 v0, v19, v0
	v_add_f32_e32 v0, v20, v0
	v_add_f32_e32 v0, v21, v0
	v_add_f32_e32 v0, v22, v0
	v_add_f32_e32 v0, v23, v0
	v_add_f32_e32 v0, v24, v0
	v_mfma_f32_32x32x16_bf16 v[34:49], v[118:121], v[86:89], v[34:49]
	v_add_f32_e32 v0, v25, v0
	v_add_f32_e32 v0, v26, v0
	v_add_f32_e32 v0, v27, v0
	v_add_f32_e32 v0, v28, v0
	v_add_f32_e32 v0, v29, v0
	v_add_f32_e32 v0, v30, v0
	v_add_f32_e32 v0, v31, v0
	v_mfma_f32_32x32x16_bf16 v[50:65], v[130:133], v[90:93], v[50:65]
	v_add_f32_e32 v0, v32, v0
	v_add_f32_e32 v0, v33, v0
	s_waitcnt lgkmcnt(0)
	v_mfma_f32_32x32x16_bf16 v[34:49], v[70:73], v[66:69], v[34:49]
	ds_read_b64_tr_b16 v[70:71], v147 offset:22720
	ds_read_b64_tr_b16 v[72:73], v147 offset:23744
	v_mfma_f32_32x32x16_bf16 v[50:65], v[102:105], v[86:89], v[50:65]
	s_nop 8
	v_add_f32_e32 v0, v34, v0
	v_add_f32_e32 v0, v35, v0
	v_add_f32_e32 v0, v36, v0
	v_add_f32_e32 v0, v37, v0
	v_add_f32_e32 v0, v38, v0
	v_add_f32_e32 v0, v39, v0
	v_add_f32_e32 v0, v40, v0
	v_add_f32_e32 v0, v41, v0
	s_waitcnt lgkmcnt(0)
	v_mfma_f32_32x32x16_bf16 v[50:65], v[70:73], v[66:69], v[50:65]
	v_add_f32_e32 v0, v42, v0
	v_add_f32_e32 v0, v43, v0
	v_add_f32_e32 v0, v44, v0
	v_add_f32_e32 v0, v45, v0
	v_add_f32_e32 v0, v46, v0
	v_add_f32_e32 v0, v47, v0
	v_add_f32_e32 v0, v48, v0
	v_add_f32_e32 v0, v49, v0
	s_nop 3
	v_add_f32_e32 v0, v50, v0
	v_add_f32_e32 v0, v51, v0
	v_add_f32_e32 v0, v52, v0
	v_add_f32_e32 v0, v53, v0
	v_add_f32_e32 v0, v54, v0
	v_add_f32_e32 v0, v55, v0
	v_add_f32_e32 v0, v56, v0
	v_add_f32_e32 v0, v57, v0
	v_add_f32_e32 v0, v58, v0
	v_add_f32_e32 v0, v59, v0
	v_add_f32_e32 v0, v60, v0
	v_add_f32_e32 v0, v61, v0
	v_and_b32_e32 v67, 64, v229
	v_add_f32_e32 v0, v62, v0
	v_xor_b32_e32 v66, 32, v229
	v_add_u32_e32 v67, 64, v67
	v_add_f32_e32 v0, v63, v0
	v_cmp_lt_i32_e32 vcc, v66, v67
	v_add_f32_e32 v0, v64, v0
	v_add_f32_e32 v0, v65, v0
	v_cndmask_b32_e32 v66, v229, v66, vcc
	v_lshlrev_b32_e32 v85, 2, v66
	ds_bpermute_b32 v66, v85, v0
	s_waitcnt lgkmcnt(0)
	v_add_f32_e32 v0, v0, v66
	v_mul_f32_e32 v84, 0x3c000000, v0
	v_pk_add_f32 v[66:67], v[46:47], v[84:85] op_sel_hi:[1,0] neg_lo:[0,1] neg_hi:[0,1]
	v_pk_add_f32 v[46:47], v[50:51], v[84:85] op_sel_hi:[1,0] neg_lo:[0,1] neg_hi:[0,1]
	v_or_b32_e32 v0, s41, v146
	s_ashr_i32 s41, s40, 31
	v_add_lshl_u32 v50, v156, s68, 7
	v_pk_add_f32 v[70:71], v[42:43], v[84:85] op_sel_hi:[1,0] neg_lo:[0,1] neg_hi:[0,1]
	v_add_u32_e32 v42, 22, v0
	s_lshl_b64 s[0:1], s[40:41], 11
	v_ashrrev_i32_e32 v51, 31, v50
	v_ashrrev_i32_e32 v43, 31, v42
	v_lshl_add_u64 v[50:51], s[0:1], 0, v[50:51]
	v_or_b32_e32 v0, s84, v157
	v_lshlrev_b64 v[42:43], 17, v[42:43]
	v_or_b32_e32 v50, v50, v155
	v_lshl_add_u64 v[42:43], s[36:37], 0, v[42:43]
	v_lshlrev_b32_e32 v0, 1, v0
	v_lshlrev_b64 v[50:51], 10, v[50:51]
	s_lshl_b32 s0, s69, 2
	v_lshl_add_u64 v[42:43], v[42:43], 0, v[0:1]
	v_lshl_add_u64 v[50:51], s[38:39], 0, v[50:51]
	s_add_u32 s0, s58, s0
	v_lshlrev_b32_e32 v0, 3, v154
	v_lshl_add_u64 v[112:113], v[50:51], 0, s[48:49]
	s_addc_u32 s1, s59, 0
	v_lshl_add_u64 v[42:43], v[42:43], 0, v[0:1]
	v_lshlrev_b32_e32 v50, 4, v154
	v_pk_add_f32 v[120:121], v[2:3], v[84:85] op_sel_hi:[1,0] neg_lo:[0,1] neg_hi:[0,1]
	v_pk_add_f32 v[72:73], v[40:41], v[84:85] op_sel_hi:[1,0] neg_lo:[0,1] neg_hi:[0,1]
	v_pk_add_f32 v[68:69], v[44:45], v[84:85] op_sel_hi:[1,0] neg_lo:[0,1] neg_hi:[0,1]
	v_pk_add_f32 v[44:45], v[52:53], v[84:85] op_sel_hi:[1,0] neg_lo:[0,1] neg_hi:[0,1]
	v_pk_add_f32 v[40:41], v[54:55], v[84:85] op_sel_hi:[1,0] neg_lo:[0,1] neg_hi:[0,1]
	global_load_dwordx2 v[114:115], v[42:43], off
	global_load_dwordx4 v[52:55], v50, s[0:1]
	global_load_dwordx2 v[146:147], v[42:43], off offset:16
	global_load_dwordx4 v[206:209], v50, s[0:1] offset:32
	global_load_dwordx2 v[180:181], v[42:43], off offset:32
	global_load_dwordx4 v[210:213], v50, s[0:1] offset:64
	global_load_dwordx2 v[240:241], v[42:43], off offset:48
	global_load_dwordx4 v[214:217], v50, s[0:1] offset:96
	global_load_dwordx2 v[244:245], v[42:43], off offset:64
	global_load_dwordx4 v[218:221], v50, s[0:1] offset:128
	global_load_dwordx2 v[184:185], v[42:43], off offset:80
	global_load_dwordx4 v[150:153], v50, s[0:1] offset:160
	global_load_dwordx2 v[186:187], v[42:43], off offset:96
	global_load_dwordx4 v[154:157], v50, s[0:1] offset:192
	global_load_dwordx2 v[188:189], v[42:43], off offset:112
	global_load_dwordx4 v[158:161], v50, s[0:1] offset:224
	global_load_dwordx2 v[190:191], v[42:43], off offset:128
	global_load_dwordx4 v[250:253], v50, s[0:1] offset:256
	global_load_dwordx2 v[192:193], v[42:43], off offset:144
	global_load_dwordx2 v[194:195], v[42:43], off offset:160
	global_load_dwordx2 v[196:197], v[42:43], off offset:176
	global_load_dwordx2 v[198:199], v[42:43], off offset:192
	global_load_dwordx2 v[200:201], v[42:43], off offset:208
	global_load_dwordx2 v[202:203], v[42:43], off offset:224
	global_load_dwordx2 v[204:205], v[42:43], off offset:240
	v_pk_add_f32 v[116:117], v[4:5], v[84:85] op_sel_hi:[1,0] neg_lo:[0,1] neg_hi:[0,1]
	v_pk_mul_f32 v[122:123], v[120:121], v[120:121]
	v_pk_mul_f32 v[118:119], v[116:117], v[116:117]
	v_lshl_add_u64 v[2:3], v[112:113], 0, v[0:1]
	v_add_f32_e32 v0, v122, v123
	v_pk_add_f32 v[128:129], v[6:7], v[84:85] op_sel_hi:[1,0] neg_lo:[0,1] neg_hi:[0,1]
	v_add_f32_e32 v0, v118, v0
	v_pk_mul_f32 v[130:131], v[128:129], v[128:129]
	v_add_f32_e32 v0, v119, v0
	v_pk_add_f32 v[112:113], v[8:9], v[84:85] op_sel_hi:[1,0] neg_lo:[0,1] neg_hi:[0,1]
	v_add_f32_e32 v0, v130, v0
	v_pk_mul_f32 v[126:127], v[112:113], v[112:113]
	v_add_f32_e32 v0, v131, v0
	v_pk_add_f32 v[134:135], v[10:11], v[84:85] op_sel_hi:[1,0] neg_lo:[0,1] neg_hi:[0,1]
	v_add_f32_e32 v0, v126, v0
	v_pk_mul_f32 v[136:137], v[134:135], v[134:135]
	v_add_f32_e32 v0, v127, v0
	v_pk_add_f32 v[132:133], v[12:13], v[84:85] op_sel_hi:[1,0] neg_lo:[0,1] neg_hi:[0,1]
	v_add_f32_e32 v0, v136, v0
	v_pk_mul_f32 v[12:13], v[132:133], v[132:133]
	v_add_f32_e32 v0, v137, v0
	v_pk_add_f32 v[140:141], v[14:15], v[84:85] op_sel_hi:[1,0] neg_lo:[0,1] neg_hi:[0,1]
	v_add_f32_e32 v0, v12, v0
	v_pk_mul_f32 v[14:15], v[140:141], v[140:141]
	v_add_f32_e32 v0, v13, v0
	v_pk_add_f32 v[16:17], v[16:17], v[84:85] op_sel_hi:[1,0] neg_lo:[0,1] neg_hi:[0,1]
	v_add_f32_e32 v0, v14, v0
	v_pk_mul_f32 v[138:139], v[16:17], v[16:17]
	v_add_f32_e32 v0, v15, v0
	v_pk_add_f32 v[18:19], v[18:19], v[84:85] op_sel_hi:[1,0] neg_lo:[0,1] neg_hi:[0,1]
	v_add_f32_e32 v0, v138, v0
	v_pk_mul_f32 v[144:145], v[18:19], v[18:19]
	v_add_f32_e32 v0, v139, v0
	v_pk_add_f32 v[20:21], v[20:21], v[84:85] op_sel_hi:[1,0] neg_lo:[0,1] neg_hi:[0,1]
	v_add_f32_e32 v0, v144, v0
	v_pk_mul_f32 v[142:143], v[20:21], v[20:21]
	v_add_f32_e32 v0, v145, v0
	v_pk_add_f32 v[10:11], v[22:23], v[84:85] op_sel_hi:[1,0] neg_lo:[0,1] neg_hi:[0,1]
	v_add_f32_e32 v0, v142, v0
	v_pk_mul_f32 v[22:23], v[10:11], v[10:11]
	v_add_f32_e32 v0, v143, v0
	v_pk_add_f32 v[8:9], v[24:25], v[84:85] op_sel_hi:[1,0] neg_lo:[0,1] neg_hi:[0,1]
	v_add_f32_e32 v0, v22, v0
	v_pk_mul_f32 v[24:25], v[8:9], v[8:9]
	v_add_f32_e32 v0, v23, v0
	v_pk_add_f32 v[6:7], v[26:27], v[84:85] op_sel_hi:[1,0] neg_lo:[0,1] neg_hi:[0,1]
	v_add_f32_e32 v0, v24, v0
	v_pk_mul_f32 v[26:27], v[6:7], v[6:7]
	v_add_f32_e32 v0, v25, v0
	v_pk_add_f32 v[4:5], v[28:29], v[84:85] op_sel_hi:[1,0] neg_lo:[0,1] neg_hi:[0,1]
	v_add_f32_e32 v0, v26, v0
	v_pk_mul_f32 v[28:29], v[4:5], v[4:5]
	v_add_f32_e32 v0, v27, v0
	v_pk_add_f32 v[82:83], v[30:31], v[84:85] op_sel_hi:[1,0] neg_lo:[0,1] neg_hi:[0,1]
	v_add_f32_e32 v0, v28, v0
	v_pk_mul_f32 v[86:87], v[82:83], v[82:83]
	v_add_f32_e32 v0, v29, v0
	v_pk_add_f32 v[80:81], v[32:33], v[84:85] op_sel_hi:[1,0] neg_lo:[0,1] neg_hi:[0,1]
	v_add_f32_e32 v0, v86, v0
	v_pk_mul_f32 v[88:89], v[80:81], v[80:81]
	v_add_f32_e32 v0, v87, v0
	v_pk_add_f32 v[78:79], v[34:35], v[84:85] op_sel_hi:[1,0] neg_lo:[0,1] neg_hi:[0,1]
	v_add_f32_e32 v0, v88, v0
	v_pk_mul_f32 v[90:91], v[78:79], v[78:79]
	v_add_f32_e32 v0, v89, v0
	v_pk_add_f32 v[76:77], v[36:37], v[84:85] op_sel_hi:[1,0] neg_lo:[0,1] neg_hi:[0,1]
	v_add_f32_e32 v0, v90, v0
	v_pk_mul_f32 v[92:93], v[76:77], v[76:77]
	v_add_f32_e32 v0, v91, v0
	v_pk_add_f32 v[74:75], v[38:39], v[84:85] op_sel_hi:[1,0] neg_lo:[0,1] neg_hi:[0,1]
	v_add_f32_e32 v0, v92, v0
	v_pk_mul_f32 v[94:95], v[74:75], v[74:75]
	v_add_f32_e32 v0, v93, v0
	v_add_f32_e32 v0, v94, v0
	v_pk_mul_f32 v[96:97], v[72:73], v[72:73]
	v_add_f32_e32 v0, v95, v0
	v_add_f32_e32 v0, v96, v0
	v_pk_mul_f32 v[98:99], v[70:71], v[70:71]
	v_add_f32_e32 v0, v97, v0
	v_add_f32_e32 v0, v98, v0
	v_pk_mul_f32 v[100:101], v[68:69], v[68:69]
	v_add_f32_e32 v0, v99, v0
	v_add_f32_e32 v0, v100, v0
	v_pk_mul_f32 v[102:103], v[66:67], v[66:67]
	v_add_f32_e32 v0, v101, v0
	v_pk_add_f32 v[48:49], v[48:49], v[84:85] op_sel_hi:[1,0] neg_lo:[0,1] neg_hi:[0,1]
	v_add_f32_e32 v0, v102, v0
	v_pk_mul_f32 v[104:105], v[48:49], v[48:49]
	v_add_f32_e32 v0, v103, v0
	v_add_f32_e32 v0, v104, v0
	v_pk_mul_f32 v[106:107], v[46:47], v[46:47]
	v_add_f32_e32 v0, v105, v0
	v_add_f32_e32 v0, v106, v0
	v_pk_mul_f32 v[108:109], v[44:45], v[44:45]
	v_add_f32_e32 v0, v107, v0
	v_add_f32_e32 v0, v108, v0
	v_pk_mul_f32 v[110:111], v[40:41], v[40:41]
	v_add_f32_e32 v0, v109, v0
	v_pk_add_f32 v[38:39], v[56:57], v[84:85] op_sel_hi:[1,0] neg_lo:[0,1] neg_hi:[0,1]
	v_add_f32_e32 v0, v110, v0
	v_pk_mul_f32 v[56:57], v[38:39], v[38:39]
	v_add_f32_e32 v0, v111, v0
	v_pk_add_f32 v[36:37], v[58:59], v[84:85] op_sel_hi:[1,0] neg_lo:[0,1] neg_hi:[0,1]
	v_add_f32_e32 v0, v56, v0
	v_pk_mul_f32 v[58:59], v[36:37], v[36:37]
	v_add_f32_e32 v0, v57, v0
	v_pk_add_f32 v[34:35], v[60:61], v[84:85] op_sel_hi:[1,0] neg_lo:[0,1] neg_hi:[0,1]
	v_add_f32_e32 v0, v58, v0
	v_pk_mul_f32 v[60:61], v[34:35], v[34:35]
	v_add_f32_e32 v0, v59, v0
	v_pk_add_f32 v[32:33], v[62:63], v[84:85] op_sel_hi:[1,0] neg_lo:[0,1] neg_hi:[0,1]
	v_add_f32_e32 v0, v60, v0
	v_pk_mul_f32 v[62:63], v[32:33], v[32:33]
	v_add_f32_e32 v0, v61, v0
	v_pk_add_f32 v[30:31], v[64:65], v[84:85] op_sel_hi:[1,0] neg_lo:[0,1] neg_hi:[0,1]
	v_add_f32_e32 v0, v62, v0
	v_pk_mul_f32 v[64:65], v[30:31], v[30:31]
	v_add_f32_e32 v0, v63, v0
	v_add_f32_e32 v0, v64, v0
	v_add_f32_e32 v0, v65, v0
	ds_bpermute_b32 v12, v85, v0
	s_waitcnt vmcnt(24)
	global_load_dwordx4 v[88:91], v50, s[0:1] offset:288
	global_load_dwordx4 v[92:95], v50, s[0:1] offset:320
	global_load_dwordx4 v[96:99], v50, s[0:1] offset:352
	global_load_dwordx4 v[100:103], v50, s[0:1] offset:384
	global_load_dwordx4 v[104:107], v50, s[0:1] offset:416
	global_load_dwordx4 v[136:139], v50, s[0:1] offset:448
	global_load_dwordx4 v[142:145], v50, s[0:1] offset:480
	v_lshlrev_b32_e32 v124, 16, v114
	v_and_b32_e32 v125, 0xffff0000, v114
	v_lshlrev_b32_e32 v114, 16, v115
	v_and_b32_e32 v115, 0xffff0000, v115
	s_waitcnt lgkmcnt(0)
	v_add_f32_e32 v0, v0, v12
	v_fmamk_f32 v0, v0, 0x3c000000, v234
	v_cmp_gt_f32_e32 vcc, s95, v0
	v_mul_f32_e32 v12, 0x4b800000, v0
	s_add_i32 s63, s63, s92
	v_cndmask_b32_e32 v0, v0, v12, vcc
	v_rsq_f32_e32 v0, v0
	s_cmpk_gt_i32 s63, 0x1ff
	v_mul_f32_e32 v12, 0x45800000, v0
	v_cndmask_b32_e32 v0, v0, v12, vcc
	v_pk_mul_f32 v[12:13], v[120:121], v[0:1] op_sel_hi:[1,0]
	v_pk_mul_f32 v[14:15], v[116:117], v[0:1] op_sel_hi:[1,0]
	s_waitcnt vmcnt(30)
	v_pk_mul_f32 v[12:13], v[52:53], v[12:13]
	v_pk_mul_f32 v[14:15], v[54:55], v[14:15]
	v_pk_mul_f32 v[12:13], v[12:13], v[124:125]
	v_pk_mul_f32 v[14:15], v[14:15], v[114:115]
	v_cvt_pk_bf16_f32 v12, v12, v13
	v_cvt_pk_bf16_f32 v13, v14, v15
	global_store_dwordx2 v[2:3], v[12:13], off
	v_pk_mul_f32 v[24:25], v[128:129], v[0:1] op_sel_hi:[1,0]
	v_pk_mul_f32 v[16:17], v[16:17], v[0:1] op_sel_hi:[1,0]
	v_pk_mul_f32 v[18:19], v[18:19], v[0:1] op_sel_hi:[1,0]
	v_pk_mul_f32 v[10:11], v[10:11], v[0:1] op_sel_hi:[1,0]
	v_pk_mul_f32 v[8:9], v[8:9], v[0:1] op_sel_hi:[1,0]
	v_pk_mul_f32 v[6:7], v[6:7], v[0:1] op_sel_hi:[1,0]
	v_pk_mul_f32 v[4:5], v[4:5], v[0:1] op_sel_hi:[1,0]
	s_waitcnt vmcnt(29)
	v_pk_mul_f32 v[206:207], v[206:207], v[24:25]
	v_lshlrev_b32_e32 v24, 16, v146
	v_and_b32_e32 v25, 0xffff0000, v146
	v_pk_mul_f32 v[206:207], v[206:207], v[24:25]
	v_pk_mul_f32 v[24:25], v[112:113], v[0:1] op_sel_hi:[1,0]
	v_lshlrev_b32_e32 v146, 16, v147
	v_pk_mul_f32 v[208:209], v[208:209], v[24:25]
	v_and_b32_e32 v147, 0xffff0000, v147
	v_pk_mul_f32 v[208:209], v[208:209], v[146:147]
	v_cvt_pk_bf16_f32 v206, v206, v207
	v_cvt_pk_bf16_f32 v207, v208, v209
	global_store_dwordx2 v[2:3], v[206:207], off offset:16
	v_pk_mul_f32 v[24:25], v[134:135], v[0:1] op_sel_hi:[1,0]
	s_waitcnt vmcnt(28)
	v_pk_mul_f32 v[210:211], v[210:211], v[24:25]
	v_lshlrev_b32_e32 v24, 16, v180
	v_and_b32_e32 v25, 0xffff0000, v180
	v_pk_mul_f32 v[210:211], v[210:211], v[24:25]
	v_pk_mul_f32 v[24:25], v[132:133], v[0:1] op_sel_hi:[1,0]
	v_lshlrev_b32_e32 v180, 16, v181
	v_pk_mul_f32 v[212:213], v[212:213], v[24:25]
	v_and_b32_e32 v181, 0xffff0000, v181
	v_pk_mul_f32 v[212:213], v[212:213], v[180:181]
	v_cvt_pk_bf16_f32 v210, v210, v211
	v_cvt_pk_bf16_f32 v211, v212, v213
	global_store_dwordx2 v[2:3], v[210:211], off offset:32
	v_pk_mul_f32 v[24:25], v[140:141], v[0:1] op_sel_hi:[1,0]
	s_waitcnt vmcnt(27)
	v_pk_mul_f32 v[216:217], v[216:217], v[16:17]
	v_pk_mul_f32 v[214:215], v[214:215], v[24:25]
	v_lshlrev_b32_e32 v24, 16, v240
	v_and_b32_e32 v25, 0xffff0000, v240
	v_lshlrev_b32_e32 v16, 16, v241
	v_and_b32_e32 v17, 0xffff0000, v241
	v_pk_mul_f32 v[214:215], v[214:215], v[24:25]
	v_pk_mul_f32 v[216:217], v[216:217], v[16:17]
	v_cvt_pk_bf16_f32 v214, v214, v215
	v_cvt_pk_bf16_f32 v215, v216, v217
	global_store_dwordx2 v[2:3], v[214:215], off offset:48
	s_waitcnt vmcnt(26)
	v_pk_mul_f32 v[218:219], v[218:219], v[18:19]
	v_lshlrev_b32_e32 v18, 16, v244
	v_and_b32_e32 v19, 0xffff0000, v244
	v_pk_mul_f32 v[218:219], v[218:219], v[18:19]
	v_pk_mul_f32 v[18:19], v[20:21], v[0:1] op_sel_hi:[1,0]
	v_lshlrev_b32_e32 v244, 16, v245
	v_pk_mul_f32 v[220:221], v[220:221], v[18:19]
	v_and_b32_e32 v245, 0xffff0000, v245
	v_pk_mul_f32 v[220:221], v[220:221], v[244:245]
	v_cvt_pk_bf16_f32 v218, v218, v219
	v_cvt_pk_bf16_f32 v219, v220, v221
	global_store_dwordx2 v[2:3], v[218:219], off offset:64
	s_waitcnt vmcnt(25)
	v_pk_mul_f32 v[10:11], v[150:151], v[10:11]
	v_lshlrev_b32_e32 v150, 16, v184
	v_and_b32_e32 v151, 0xffff0000, v184
	v_pk_mul_f32 v[10:11], v[10:11], v[150:151]
	v_pk_mul_f32 v[8:9], v[152:153], v[8:9]
	v_lshlrev_b32_e32 v150, 16, v185
	v_and_b32_e32 v151, 0xffff0000, v185
	v_pk_mul_f32 v[8:9], v[8:9], v[150:151]
	v_cvt_pk_bf16_f32 v10, v10, v11
	v_cvt_pk_bf16_f32 v11, v8, v9
	global_store_dwordx2 v[2:3], v[10:11], off offset:80
	s_waitcnt vmcnt(24)
	v_pk_mul_f32 v[6:7], v[154:155], v[6:7]
	v_lshlrev_b32_e32 v154, 16, v186
	v_and_b32_e32 v155, 0xffff0000, v186
	v_pk_mul_f32 v[6:7], v[6:7], v[154:155]
	v_pk_mul_f32 v[4:5], v[156:157], v[4:5]
	v_lshlrev_b32_e32 v154, 16, v187
	v_and_b32_e32 v155, 0xffff0000, v187
	v_pk_mul_f32 v[4:5], v[4:5], v[154:155]
	v_cvt_pk_bf16_f32 v6, v6, v7
	v_cvt_pk_bf16_f32 v7, v4, v5
	global_store_dwordx2 v[2:3], v[6:7], off offset:96
	v_pk_mul_f32 v[10:11], v[82:83], v[0:1] op_sel_hi:[1,0]
	s_waitcnt vmcnt(23)
	v_pk_mul_f32 v[158:159], v[158:159], v[10:11]
	v_lshlrev_b32_e32 v10, 16, v188
	v_and_b32_e32 v11, 0xffff0000, v188
	v_pk_mul_f32 v[158:159], v[158:159], v[10:11]
	v_pk_mul_f32 v[10:11], v[80:81], v[0:1] op_sel_hi:[1,0]
	v_lshlrev_b32_e32 v188, 16, v189
	v_pk_mul_f32 v[160:161], v[160:161], v[10:11]
	v_and_b32_e32 v189, 0xffff0000, v189
	v_pk_mul_f32 v[160:161], v[160:161], v[188:189]
	v_cvt_pk_bf16_f32 v158, v158, v159
	v_cvt_pk_bf16_f32 v159, v160, v161
	global_store_dwordx2 v[2:3], v[158:159], off offset:112
	v_pk_mul_f32 v[10:11], v[78:79], v[0:1] op_sel_hi:[1,0]
	s_waitcnt vmcnt(22)
	v_pk_mul_f32 v[250:251], v[250:251], v[10:11]
	v_lshlrev_b32_e32 v10, 16, v190
	v_and_b32_e32 v11, 0xffff0000, v190
	v_pk_mul_f32 v[250:251], v[250:251], v[10:11]
	v_pk_mul_f32 v[10:11], v[76:77], v[0:1] op_sel_hi:[1,0]
	v_lshlrev_b32_e32 v190, 16, v191
	v_pk_mul_f32 v[252:253], v[252:253], v[10:11]
	v_and_b32_e32 v191, 0xffff0000, v191
	v_pk_mul_f32 v[252:253], v[252:253], v[190:191]
	v_cvt_pk_bf16_f32 v250, v250, v251
	v_cvt_pk_bf16_f32 v251, v252, v253
	global_store_dwordx2 v[2:3], v[250:251], off offset:128
	v_pk_mul_f32 v[10:11], v[74:75], v[0:1] op_sel_hi:[1,0]
	s_waitcnt vmcnt(15)
	v_pk_mul_f32 v[88:89], v[88:89], v[10:11]
	v_lshlrev_b32_e32 v10, 16, v192
	v_and_b32_e32 v11, 0xffff0000, v192
	v_pk_mul_f32 v[88:89], v[88:89], v[10:11]
	v_pk_mul_f32 v[10:11], v[72:73], v[0:1] op_sel_hi:[1,0]
	v_lshlrev_b32_e32 v192, 16, v193
	v_pk_mul_f32 v[90:91], v[90:91], v[10:11]
	v_and_b32_e32 v193, 0xffff0000, v193
	v_pk_mul_f32 v[90:91], v[90:91], v[192:193]
	v_cvt_pk_bf16_f32 v88, v88, v89
	v_cvt_pk_bf16_f32 v89, v90, v91
	global_store_dwordx2 v[2:3], v[88:89], off offset:144
	v_pk_mul_f32 v[10:11], v[70:71], v[0:1] op_sel_hi:[1,0]
	s_waitcnt vmcnt(15)
	v_pk_mul_f32 v[92:93], v[92:93], v[10:11]
	v_lshlrev_b32_e32 v10, 16, v194
	v_and_b32_e32 v11, 0xffff0000, v194
	v_pk_mul_f32 v[92:93], v[92:93], v[10:11]
	v_pk_mul_f32 v[10:11], v[68:69], v[0:1] op_sel_hi:[1,0]
	v_lshlrev_b32_e32 v194, 16, v195
	v_pk_mul_f32 v[94:95], v[94:95], v[10:11]
	v_and_b32_e32 v195, 0xffff0000, v195
	v_pk_mul_f32 v[94:95], v[94:95], v[194:195]
	v_cvt_pk_bf16_f32 v92, v92, v93
	v_cvt_pk_bf16_f32 v93, v94, v95
	global_store_dwordx2 v[2:3], v[92:93], off offset:160
	v_pk_mul_f32 v[10:11], v[66:67], v[0:1] op_sel_hi:[1,0]
	s_waitcnt vmcnt(15)
	v_pk_mul_f32 v[96:97], v[96:97], v[10:11]
	v_lshlrev_b32_e32 v10, 16, v196
	v_and_b32_e32 v11, 0xffff0000, v196
	v_pk_mul_f32 v[96:97], v[96:97], v[10:11]
	v_pk_mul_f32 v[10:11], v[48:49], v[0:1] op_sel_hi:[1,0]
	v_lshlrev_b32_e32 v196, 16, v197
	v_pk_mul_f32 v[98:99], v[98:99], v[10:11]
	v_and_b32_e32 v197, 0xffff0000, v197
	v_pk_mul_f32 v[98:99], v[98:99], v[196:197]
	v_cvt_pk_bf16_f32 v96, v96, v97
	v_cvt_pk_bf16_f32 v97, v98, v99
	global_store_dwordx2 v[2:3], v[96:97], off offset:176
	v_pk_mul_f32 v[10:11], v[46:47], v[0:1] op_sel_hi:[1,0]
	s_waitcnt vmcnt(15)
	v_pk_mul_f32 v[100:101], v[100:101], v[10:11]
	v_lshlrev_b32_e32 v10, 16, v198
	v_and_b32_e32 v11, 0xffff0000, v198
	v_pk_mul_f32 v[100:101], v[100:101], v[10:11]
	v_pk_mul_f32 v[10:11], v[44:45], v[0:1] op_sel_hi:[1,0]
	v_lshlrev_b32_e32 v198, 16, v199
	v_pk_mul_f32 v[102:103], v[102:103], v[10:11]
	v_and_b32_e32 v199, 0xffff0000, v199
	v_pk_mul_f32 v[102:103], v[102:103], v[198:199]
	v_cvt_pk_bf16_f32 v100, v100, v101
	v_cvt_pk_bf16_f32 v101, v102, v103
	global_store_dwordx2 v[2:3], v[100:101], off offset:192
	v_pk_mul_f32 v[10:11], v[40:41], v[0:1] op_sel_hi:[1,0]
	s_waitcnt vmcnt(15)
	v_pk_mul_f32 v[104:105], v[104:105], v[10:11]
	v_lshlrev_b32_e32 v10, 16, v200
	v_and_b32_e32 v11, 0xffff0000, v200
	v_pk_mul_f32 v[104:105], v[104:105], v[10:11]
	v_pk_mul_f32 v[10:11], v[38:39], v[0:1] op_sel_hi:[1,0]
	v_lshlrev_b32_e32 v200, 16, v201
	v_pk_mul_f32 v[106:107], v[106:107], v[10:11]
	v_and_b32_e32 v201, 0xffff0000, v201
	v_pk_mul_f32 v[106:107], v[106:107], v[200:201]
	v_cvt_pk_bf16_f32 v104, v104, v105
	v_cvt_pk_bf16_f32 v105, v106, v107
	global_store_dwordx2 v[2:3], v[104:105], off offset:208
	v_pk_mul_f32 v[10:11], v[36:37], v[0:1] op_sel_hi:[1,0]
	s_waitcnt vmcnt(15)
	v_pk_mul_f32 v[136:137], v[136:137], v[10:11]
	v_lshlrev_b32_e32 v10, 16, v202
	v_and_b32_e32 v11, 0xffff0000, v202
	v_pk_mul_f32 v[136:137], v[136:137], v[10:11]
	v_pk_mul_f32 v[10:11], v[34:35], v[0:1] op_sel_hi:[1,0]
	v_lshlrev_b32_e32 v202, 16, v203
	v_pk_mul_f32 v[138:139], v[138:139], v[10:11]
	v_and_b32_e32 v203, 0xffff0000, v203
	v_pk_mul_f32 v[138:139], v[138:139], v[202:203]
	v_cvt_pk_bf16_f32 v136, v136, v137
	v_cvt_pk_bf16_f32 v137, v138, v139
	global_store_dwordx2 v[2:3], v[136:137], off offset:224
	v_pk_mul_f32 v[10:11], v[32:33], v[0:1] op_sel_hi:[1,0]
	s_waitcnt vmcnt(15)
	v_pk_mul_f32 v[142:143], v[142:143], v[10:11]
	v_lshlrev_b32_e32 v10, 16, v204
	v_and_b32_e32 v11, 0xffff0000, v204
	v_pk_mul_f32 v[142:143], v[142:143], v[10:11]
	v_pk_mul_f32 v[10:11], v[30:31], v[0:1] op_sel_hi:[1,0]
	v_lshlrev_b32_e32 v204, 16, v205
	v_pk_mul_f32 v[144:145], v[144:145], v[10:11]
	v_and_b32_e32 v205, 0xffff0000, v205
	v_pk_mul_f32 v[144:145], v[144:145], v[204:205]
	v_cvt_pk_bf16_f32 v142, v142, v143
	v_cvt_pk_bf16_f32 v143, v144, v145
	global_store_dwordx2 v[2:3], v[142:143], off offset:240
	s_barrier
	s_cbranch_scc1 .LBB0_450
.LBB0_437:
	s_bfe_u32 s85, s63, 0x20003
	s_lshl_b32 s1, s63, 1
	s_and_b32 s68, s1, 14
	s_lshl_b32 s1, s85, 2
	v_mov_b32_e32 v46, v230
	v_mov_b32_e32 v0, s1
	global_load_dword v2, v0, s[56:57]
	global_load_dword v47, v0, s[56:57] offset:16
	s_ashr_i32 s40, s63, 5
	s_lshl_b32 s69, s85, 7
	s_lshl_b32 s1, s40, 11
	s_lshl_b32 s6, s68, 7
	v_and_b32_e32 v0, 15, v46
	s_and_b32 s84, s69, 0x80
	s_lshr_b32 s0, s63, 3
	s_or_b32 s89, s6, s1
	s_bfe_u32 s41, s0, 0x10001
	s_or_b32 s0, s41, 20
	s_lshl_b32 s1, s85, 4
	s_waitcnt vmcnt(0)
	v_mul_f32_e32 v3, 0xbfb8aa3b, v2
	v_fma_f32 v4, v2, s61, -v3
	v_rndne_f32_e32 v5, v3
	v_fmac_f32_e32 v4, 0xb2a5705f, v2
	v_sub_f32_e32 v3, v3, v5
	v_add_f32_e32 v3, v3, v4
	v_exp_f32_e32 v3, v3
	v_cvt_i32_f32_e32 v4, v5
	v_cmp_nlt_f32_e32 vcc, s74, v2
	v_ldexp_f32 v3, v3, v4
	s_nop 0
	v_cndmask_b32_e32 v3, 0, v3, vcc
	v_cmp_ngt_f32_e32 vcc, s75, v2
	s_nop 1
	v_cndmask_b32_e32 v4, v235, v3, vcc
	v_add_f32_e32 v5, 1.0, v4
	v_add_f32_e32 v2, -1.0, v5
	v_sub_f32_e32 v3, v2, v5
	v_add_f32_e32 v3, 1.0, v3
	v_sub_f32_e32 v2, v4, v2
	v_add_f32_e32 v6, v2, v3
	v_frexp_mant_f32_e32 v2, v5
	v_cmp_gt_f32_e32 vcc, s77, v2
	v_cvt_f64_f32_e32 v[2:3], v5
	v_frexp_exp_i32_f64_e32 v2, v[2:3]
	v_subbrev_co_u32_e32 v2, vcc, 0, v2, vcc
	v_sub_u32_e32 v3, 0, v2
	v_ldexp_f32 v5, v5, v3
	v_ldexp_f32 v3, v6, v3
	v_add_f32_e32 v6, -1.0, v5
	v_add_f32_e32 v7, 1.0, v6
	v_sub_f32_e32 v7, v5, v7
	v_add_f32_e32 v7, v3, v7
	v_add_f32_e32 v8, v6, v7
	v_sub_f32_e32 v6, v6, v8
	v_add_f32_e32 v6, v7, v6
	v_add_f32_e32 v7, 1.0, v5
	v_add_f32_e32 v9, -1.0, v7
	v_sub_f32_e32 v5, v5, v9
	v_add_f32_e32 v3, v3, v5
	v_add_f32_e32 v5, v7, v3
	v_sub_f32_e32 v7, v7, v5
	v_add_f32_e32 v3, v3, v7
	v_rcp_f32_e32 v7, v5
	v_cvt_f32_i32_e32 v2, v2
	v_cmp_neq_f32_e32 vcc, s76, v4
	v_mul_f32_e32 v9, v8, v7
	v_mul_f32_e32 v10, v5, v9
	v_fma_f32 v11, v9, v5, -v10
	v_fmac_f32_e32 v11, v9, v3
	v_add_f32_e32 v12, v10, v11
	v_sub_f32_e32 v13, v8, v12
	v_sub_f32_e32 v8, v8, v13
	v_sub_f32_e32 v10, v12, v10
	v_sub_f32_e32 v8, v8, v12
	v_add_f32_e32 v6, v6, v8
	v_sub_f32_e32 v8, v10, v11
	v_add_f32_e32 v6, v8, v6
	v_add_f32_e32 v8, v13, v6
	v_mul_f32_e32 v10, v7, v8
	v_mul_f32_e32 v11, v5, v10
	v_fma_f32 v5, v10, v5, -v11
	v_fmac_f32_e32 v5, v10, v3
	v_sub_f32_e32 v3, v13, v8
	v_add_f32_e32 v3, v6, v3
	v_add_f32_e32 v6, v11, v5
	v_sub_f32_e32 v12, v8, v6
	v_sub_f32_e32 v8, v8, v12
	v_sub_f32_e32 v11, v6, v11
	v_sub_f32_e32 v6, v8, v6
	v_add_f32_e32 v3, v3, v6
	v_sub_f32_e32 v5, v11, v5
	v_add_f32_e32 v3, v5, v3
	v_add_f32_e32 v5, v9, v10
	v_add_f32_e32 v3, v12, v3
	v_sub_f32_e32 v6, v5, v9
	v_mul_f32_e32 v3, v7, v3
	v_sub_f32_e32 v6, v10, v6
	v_add_f32_e32 v3, v6, v3
	v_mul_f32_e32 v9, 0x3f317218, v2
	v_add_f32_e32 v6, v5, v3
	v_fma_f32 v10, v2, s86, -v9
	v_mul_f32_e32 v7, v6, v6
	v_fmac_f32_e32 v10, 0xb102e308, v2
	v_sub_f32_e32 v2, v6, v5
	v_fmamk_f32 v8, v7, 0x3e9b6dac, v232
	v_sub_f32_e32 v2, v3, v2
	v_add_f32_e32 v3, v9, v10
	v_fmaak_f32 v8, v7, v8, 0x3f2aaada
	v_sub_f32_e32 v5, v3, v9
	v_ldexp_f32 v9, v6, 1
	v_mul_f32_e32 v6, v6, v7
	v_mul_f32_e32 v6, v6, v8
	v_add_f32_e32 v7, v9, v6
	v_sub_f32_e32 v8, v7, v9
	v_ldexp_f32 v2, v2, 1
	v_sub_f32_e32 v6, v6, v8
	v_add_f32_e32 v2, v2, v6
	v_add_f32_e32 v6, v7, v2
	v_sub_f32_e32 v7, v6, v7
	v_sub_f32_e32 v2, v2, v7
	v_add_f32_e32 v7, v3, v6
	v_sub_f32_e32 v8, v7, v3
	v_sub_f32_e32 v9, v7, v8
	v_sub_f32_e32 v5, v10, v5
	v_sub_f32_e32 v3, v3, v9
	v_sub_f32_e32 v6, v6, v8
	v_add_f32_e32 v3, v6, v3
	v_add_f32_e32 v6, v5, v2
	v_sub_f32_e32 v8, v6, v5
	v_sub_f32_e32 v9, v6, v8
	v_sub_f32_e32 v5, v5, v9
	v_sub_f32_e32 v2, v2, v8
	v_add_f32_e32 v3, v6, v3
	v_add_f32_e32 v2, v2, v5
	v_add_f32_e32 v5, v7, v3
	v_sub_f32_e32 v6, v5, v7
	v_sub_f32_e32 v3, v3, v6
	v_add_f32_e32 v2, v2, v3
	v_add_f32_e32 v2, v5, v2
	v_cndmask_b32_e32 v2, v235, v2, vcc
	v_cmp_lt_f32_e64 vcc, |v4|, s87
	v_lshl_add_u32 v7, v0, 4, 0
	s_nop 0
	v_cndmask_b32_e32 v6, v2, v4, vcc
	v_lshl_or_b32 v4, v0, 3, s84
	v_ashrrev_i32_e32 v0, 4, v46
	v_add_u32_e32 v2, s89, v0
	v_lshrrev_b32_e32 v2, 8, v2
	v_mad_i32_i24 v2, v2, 38, s0
	v_ashrrev_i32_e32 v3, 31, v2
	v_lshlrev_b32_e32 v5, 8, v0
	v_and_or_b32 v0, v5, s60, v4
	v_lshlrev_b64 v[2:3], 17, v[2:3]
	v_lshl_add_u64 v[2:3], s[36:37], 0, v[2:3]
	v_lshlrev_b32_e32 v0, 1, v0
	v_lshl_add_u64 v[2:3], v[2:3], 0, v[0:1]
	global_load_dwordx4 v[184:187], v[2:3], off
	v_add_u32_e32 v216, v7, v5
	v_mul_f32_e32 v108, 0xbfb8aa3b, v6
	v_add_u32_e32 v0, 0x200, v46
	v_ashrrev_i32_e32 v0, 4, v0
	v_add_u32_e32 v2, s89, v0
	v_lshrrev_b32_e32 v2, 8, v2
	v_mad_i32_i24 v2, v2, 38, s0
	v_ashrrev_i32_e32 v3, 31, v2
	v_lshlrev_b32_e32 v5, 8, v0
	v_and_or_b32 v0, v5, s60, v4
	v_lshlrev_b64 v[2:3], 17, v[2:3]
	v_lshl_add_u64 v[2:3], s[36:37], 0, v[2:3]
	v_lshlrev_b32_e32 v0, 1, v0
	v_lshl_add_u64 v[2:3], v[2:3], 0, v[0:1]
	global_load_dwordx4 v[188:191], v[2:3], off
	v_add_u32_e32 v217, v7, v5
	v_add_u32_e32 v0, 0x400, v46
	v_ashrrev_i32_e32 v0, 4, v0
	v_add_u32_e32 v2, s89, v0
	v_lshrrev_b32_e32 v2, 8, v2
	v_mad_i32_i24 v2, v2, 38, s0
	v_ashrrev_i32_e32 v3, 31, v2
	v_lshlrev_b32_e32 v5, 8, v0
	v_and_or_b32 v0, v5, s60, v4
	v_lshlrev_b64 v[2:3], 17, v[2:3]
	v_lshl_add_u64 v[2:3], s[36:37], 0, v[2:3]
	v_lshlrev_b32_e32 v0, 1, v0
	v_lshl_add_u64 v[2:3], v[2:3], 0, v[0:1]
	global_load_dwordx4 v[192:195], v[2:3], off
	v_add_u32_e32 v218, v7, v5
	v_add_u32_e32 v0, 0x600, v46
	v_ashrrev_i32_e32 v0, 4, v0
	v_add_u32_e32 v2, s89, v0
	v_lshrrev_b32_e32 v2, 8, v2
	v_mad_i32_i24 v2, v2, 38, s0
	v_ashrrev_i32_e32 v3, 31, v2
	v_lshlrev_b32_e32 v5, 8, v0
	v_and_or_b32 v0, v5, s60, v4
	v_lshlrev_b64 v[2:3], 17, v[2:3]
	v_lshl_add_u64 v[2:3], s[36:37], 0, v[2:3]
	v_lshlrev_b32_e32 v0, 1, v0
	v_lshl_add_u64 v[2:3], v[2:3], 0, v[0:1]
	global_load_dwordx4 v[196:199], v[2:3], off
	v_add_u32_e32 v219, v7, v5
	v_add_u32_e32 v0, 0x800, v46
	v_ashrrev_i32_e32 v0, 4, v0
	v_add_u32_e32 v2, s89, v0
	v_lshrrev_b32_e32 v2, 8, v2
	v_mad_i32_i24 v2, v2, 38, s0
	v_ashrrev_i32_e32 v3, 31, v2
	v_lshlrev_b32_e32 v5, 8, v0
	v_and_or_b32 v0, v5, s60, v4
	v_lshlrev_b64 v[2:3], 17, v[2:3]
	v_lshl_add_u64 v[2:3], s[36:37], 0, v[2:3]
	v_lshlrev_b32_e32 v0, 1, v0
	v_lshl_add_u64 v[2:3], v[2:3], 0, v[0:1]
	global_load_dwordx4 v[200:203], v[2:3], off
	v_add_u32_e32 v220, v7, v5
	v_add_u32_e32 v0, 0xa00, v46
	v_ashrrev_i32_e32 v0, 4, v0
	v_add_u32_e32 v2, s89, v0
	v_lshrrev_b32_e32 v2, 8, v2
	v_mad_i32_i24 v2, v2, 38, s0
	v_ashrrev_i32_e32 v3, 31, v2
	v_lshlrev_b32_e32 v5, 8, v0
	v_and_or_b32 v0, v5, s60, v4
	v_lshlrev_b64 v[2:3], 17, v[2:3]
	v_lshl_add_u64 v[2:3], s[36:37], 0, v[2:3]
	v_lshlrev_b32_e32 v0, 1, v0
	v_lshl_add_u64 v[2:3], v[2:3], 0, v[0:1]
	global_load_dwordx4 v[204:207], v[2:3], off
	v_add_u32_e32 v221, v7, v5
	v_add_u32_e32 v0, 0xc00, v46
	v_ashrrev_i32_e32 v0, 4, v0
	v_add_u32_e32 v2, s89, v0
	v_lshrrev_b32_e32 v2, 8, v2
	v_mad_i32_i24 v2, v2, 38, s0
	v_ashrrev_i32_e32 v3, 31, v2
	v_lshlrev_b32_e32 v5, 8, v0
	v_and_or_b32 v0, v5, s60, v4
	v_lshlrev_b64 v[2:3], 17, v[2:3]
	v_lshl_add_u64 v[2:3], s[36:37], 0, v[2:3]
	v_lshlrev_b32_e32 v0, 1, v0
	v_lshl_add_u64 v[2:3], v[2:3], 0, v[0:1]
	global_load_dwordx4 v[208:211], v[2:3], off
	v_add_u32_e32 v222, v7, v5
	v_add_u32_e32 v0, 0xe00, v46
	v_ashrrev_i32_e32 v0, 4, v0
	v_add_u32_e32 v2, s89, v0
	v_lshrrev_b32_e32 v2, 8, v2
	v_mad_i32_i24 v2, v2, 38, s0
	v_ashrrev_i32_e32 v3, 31, v2
	v_lshlrev_b32_e32 v8, 8, v0
	v_and_or_b32 v0, v8, s60, v4
	v_lshlrev_b64 v[2:3], 17, v[2:3]
	v_lshl_add_u64 v[2:3], s[36:37], 0, v[2:3]
	v_lshlrev_b32_e32 v0, 1, v0
	v_lshl_add_u64 v[2:3], v[2:3], 0, v[0:1]
	global_load_dwordx4 v[212:215], v[2:3], off
	v_add_u32_e32 v223, v7, v8
	s_lshl_b32 s0, s40, 6
	s_or_b32 s0, s1, s0
	s_ashr_i32 s1, s0, 31
	s_lshl_b64 s[0:1], s[0:1], 15
	s_add_u32 s0, s2, s0
	s_addc_u32 s1, s3, s1
	s_waitcnt vmcnt(7)
	ds_write_b128 v216, v[184:187]
	s_waitcnt vmcnt(6)
	ds_write_b128 v217, v[188:191]
	s_waitcnt vmcnt(5)
	ds_write_b128 v218, v[192:195]
	s_waitcnt vmcnt(4)
	ds_write_b128 v219, v[196:199]
	s_waitcnt vmcnt(3)
	ds_write_b128 v220, v[200:203]
	s_waitcnt vmcnt(2)
	ds_write_b128 v221, v[204:207]
	s_waitcnt vmcnt(1)
	ds_write_b128 v222, v[208:211]
	s_waitcnt vmcnt(0)
	ds_write_b128 v223, v[212:215]
	v_mul_f32_e32 v0, 0x43000000, v108
	v_cmp_gt_f32_e32 vcc, s97, v0
	v_lshlrev_b32_e32 v2, 4, v46
	v_ashrrev_i32_e32 v3, 31, v2
	v_cndmask_b32_e32 v0, 0, v233, vcc
	v_fmac_f32_e32 v0, 0x43000000, v108
	v_exp_f32_e32 v0, v0
	v_lshl_add_u64 v[2:3], v[2:3], 1, s[0:1]
	s_and_b64 s[0:1], vcc, exec
	s_cselect_b32 s0, 0xffffffc0, 0
	v_ldexp_f32 v6, v0, s0
	s_add_i32 s0, s68, 3
	s_and_b32 s0, s0, 28
	s_cmp_lg_u32 s0, 0
	s_cbranch_scc0 .LBB0_441
	s_sub_i32 s0, s68, s0
	v_mov_b32_e32 v24, 0
	v_mov_b32_e32 v36, 0
	v_mov_b32_e32 v22, 0
	v_mov_b32_e32 v34, 0
	v_mov_b32_e32 v20, 0
	v_mov_b32_e32 v32, 0
	v_mov_b32_e32 v10, 0
	v_mov_b32_e32 v30, 0
	v_mov_b32_e32 v12, 0
	v_mov_b32_e32 v28, 0
	v_mov_b32_e32 v14, 0
	v_mov_b32_e32 v26, 0
	v_mov_b32_e32 v16, 0
	v_mov_b32_e32 v8, 0
	v_mov_b32_e32 v18, 0
	v_mov_b32_e32 v4, 0
